# P5 branch-merge epilogue: 8 gate-logit row loads issued up front with counted vmcnt instead of load+vmcnt(0) per row
# speedup vs baseline: 1.0554x; 1.0059x over previous
.LBB0_137:
	v_mov_b32_e32 v148, v211
	s_nop 0
	v_ashrrev_i32_e32 v146, 3, v148
	v_mad_i64_i32 v[0:1], s[20:21], v146, s38, 0
	v_lshlrev_b32_e32 v2, 4, v148
	v_and_b32_e32 v145, 0x70, v2
	s_add_u32 s20, s2, s15
	v_ashrrev_i32_e32 v147, 31, v146
	v_or_b32_e32 v0, v0, v145
	s_addc_u32 s21, s3, s13
	v_lshl_add_u64 v[12:13], s[20:21], 0, v[0:1]
	v_lshlrev_b64 v[0:1], 10, v[146:147]
	s_add_u32 s20, s2, s8
	v_or_b32_e32 v0, v0, v145
	s_addc_u32 s21, s3, s9
	v_lshl_add_u64 v[28:29], s[20:21], 0, v[0:1]
	s_mov_b32 s20, 0x28600000
	v_add_co_u32_e32 v128, vcc, s20, v12
	s_mov_b32 s20, 0x28618000
	s_nop 0
	v_addc_co_u32_e32 v129, vcc, 0, v13, vcc
	v_add_co_u32_e32 v130, vcc, s20, v12
	s_mov_b32 s20, 0x28630000
	s_nop 0
	v_addc_co_u32_e32 v131, vcc, 0, v13, vcc
	v_add_co_u32_e32 v132, vcc, s20, v12
	s_mov_b32 s20, 0x28648000
	s_nop 0
	v_addc_co_u32_e32 v133, vcc, 0, v13, vcc
	v_add_co_u32_e32 v134, vcc, s20, v12
	s_mov_b32 s20, 0x33c00000
	s_nop 0
	v_addc_co_u32_e32 v135, vcc, 0, v13, vcc
	global_load_dwordx4 v[0:3], v[128:129], off
	global_load_dwordx4 v[4:7], v[130:131], off
	v_add_co_u32_e32 v136, vcc, s20, v28
	s_mov_b32 s20, 0x33c08000
	s_nop 0
	v_addc_co_u32_e32 v137, vcc, 0, v29, vcc
	global_load_dwordx4 v[8:11], v[132:133], off
	global_load_dwordx4 v[12:15], v[134:135], off
	v_add_co_u32_e32 v138, vcc, s20, v28
	s_mov_b32 s20, 0x33c10000
	s_nop 0
	v_addc_co_u32_e32 v139, vcc, 0, v29, vcc
	global_load_dwordx4 v[16:19], v[136:137], off
	global_load_dwordx4 v[20:23], v[138:139], off
	v_add_co_u32_e32 v140, vcc, s20, v28
	s_mov_b32 s20, 0x33c18000
	s_nop 0
	v_addc_co_u32_e32 v141, vcc, 0, v29, vcc
	global_load_dwordx4 v[24:27], v[140:141], off
	v_add_co_u32_e32 v142, vcc, s20, v28
	v_mul_u32_u24_e32 v146, 0xa0, v146
	s_nop 0
	v_addc_co_u32_e32 v143, vcc, 0, v29, vcc
	global_load_dwordx4 v[28:31], v[142:143], off
	global_load_dwordx4 v[56:59], v[128:129], off offset:128
	global_load_dwordx4 v[60:63], v[130:131], off offset:128
	global_load_dwordx4 v[44:47], v[132:133], off offset:128
	global_load_dwordx4 v[48:51], v[134:135], off offset:128
	global_load_dwordx4 v[52:55], v[136:137], off offset:128
	global_load_dwordx4 v[32:35], v[138:139], off offset:128
	global_load_dwordx4 v[36:39], v[140:141], off offset:128
	global_load_dwordx4 v[40:43], v[142:143], off offset:128
	v_add3_u32 v145, 0, v146, v145
	s_barrier
	s_add_u32 s20, s17, s6
	s_addc_u32 s21, s18, s7
	s_waitcnt vmcnt(15)
	ds_write_b128 v145, v[0:3]
	s_waitcnt vmcnt(14)
	ds_write_b128 v145, v[4:7] offset:5120
	s_waitcnt vmcnt(13)
	ds_write_b128 v145, v[8:11] offset:10240
	s_waitcnt vmcnt(12)
	ds_write_b128 v145, v[12:15] offset:15360
	s_waitcnt vmcnt(11)
	ds_write_b128 v145, v[16:19] offset:20480
	s_waitcnt vmcnt(10)
	ds_write_b128 v145, v[20:23] offset:25600
	s_waitcnt vmcnt(9)
	ds_write_b128 v145, v[24:27] offset:30720
	s_waitcnt vmcnt(8)
	ds_write_b128 v145, v[28:31] offset:35840
	v_and_b32_e32 v0, 15, v148
	v_lshrrev_b32_e32 v1, 1, v148
	v_and_or_b32 v0, v1, s43, v0
	v_mul_u32_u24_e32 v0, 0xa0, v0
	v_and_b32_e32 v1, 48, v148
	v_add3_u32 v146, 0, v0, v1
	v_and_b32_e32 v0, 0x4f, v148
	v_mul_u32_u24_e32 v0, 0x50, v0
	v_lshlrev_b32_e32 v0, 1, v0
	s_waitcnt lgkmcnt(0)
	s_barrier
	v_add3_u32 v147, 0, v0, v1
	v_add_u32_e32 v147, 0x5000, v147
	global_load_dwordx4 v[0:3], v[128:129], off offset:256
	global_load_dwordx4 v[4:7], v[130:131], off offset:256
	global_load_dwordx4 v[8:11], v[132:133], off offset:256
	global_load_dwordx4 v[12:15], v[134:135], off offset:256
	global_load_dwordx4 v[16:19], v[136:137], off offset:256
	global_load_dwordx4 v[20:23], v[138:139], off offset:256
	global_load_dwordx4 v[24:27], v[140:141], off offset:256
	global_load_dwordx4 v[28:31], v[142:143], off offset:256
	ds_read_b128 v[150:153], v146
	ds_read_b128 v[154:157], v146 offset:2560
	ds_read_b128 v[158:161], v146 offset:5120
	ds_read_b128 v[162:165], v146 offset:7680
	ds_read_b128 v[166:169], v147
	ds_read_b128 v[170:173], v147 offset:2560
	ds_read_b128 v[174:177], v147 offset:5120
	ds_read_b128 v[178:181], v147 offset:7680
	v_add_u32_e32 v148, 0xf000, v145
	s_waitcnt lgkmcnt(3)
	v_mfma_f32_16x16x32_bf16 v[182:185], v[150:153], v[166:169], 0
	s_waitcnt lgkmcnt(2)
	v_mfma_f32_16x16x32_bf16 v[186:189], v[150:153], v[170:173], 0
	s_waitcnt lgkmcnt(1)
	v_mfma_f32_16x16x32_bf16 v[190:193], v[150:153], v[174:177], 0
	s_waitcnt lgkmcnt(0)
	v_mfma_f32_16x16x32_bf16 v[150:153], v[150:153], v[178:181], 0
	v_mfma_f32_16x16x32_bf16 v[194:197], v[154:157], v[166:169], 0
	v_mfma_f32_16x16x32_bf16 v[198:201], v[154:157], v[170:173], 0
	v_mfma_f32_16x16x32_bf16 v[202:205], v[154:157], v[174:177], 0
	v_mfma_f32_16x16x32_bf16 v[154:157], v[154:157], v[178:181], 0
	v_mfma_f32_16x16x32_bf16 v[212:215], v[158:161], v[166:169], 0
	v_mfma_f32_16x16x32_bf16 v[224:227], v[158:161], v[170:173], 0
	v_mfma_f32_16x16x32_bf16 v[228:231], v[158:161], v[174:177], 0
	v_mfma_f32_16x16x32_bf16 v[158:161], v[158:161], v[178:181], 0
	v_mfma_f32_16x16x32_bf16 v[166:169], v[162:165], v[166:169], 0
	v_mfma_f32_16x16x32_bf16 v[170:173], v[162:165], v[170:173], 0
	v_mfma_f32_16x16x32_bf16 v[174:177], v[162:165], v[174:177], 0
	v_mfma_f32_16x16x32_bf16 v[162:165], v[162:165], v[178:181], 0
	ds_read_b128 v[178:181], v146 offset:64
	ds_read_b128 v[232:235], v146 offset:2624
	ds_read_b128 v[236:239], v146 offset:5184
	ds_read_b128 v[240:243], v146 offset:7744
	ds_read_b128 v[244:247], v147 offset:64
	ds_read_b128 v[248:251], v147 offset:2624
	ds_read_b128 v[216:219], v147 offset:5184
	ds_read_b128 v[220:223], v147 offset:7744
	s_waitcnt vmcnt(15)
	ds_write_b128 v145, v[56:59] offset:40960
	s_waitcnt vmcnt(14)
	ds_write_b128 v145, v[60:63] offset:46080
	s_waitcnt vmcnt(13)
	ds_write_b128 v145, v[44:47] offset:51200
	s_waitcnt vmcnt(12)
	ds_write_b128 v145, v[48:51] offset:56320
	s_waitcnt vmcnt(11)
	ds_write_b128 v145, v[52:55] offset:61440
	s_waitcnt vmcnt(10)
	ds_write_b128 v148, v[32:35] offset:5120
	s_waitcnt vmcnt(9)
	ds_write_b128 v148, v[36:39] offset:10240
	s_waitcnt vmcnt(8)
	ds_write_b128 v148, v[40:43] offset:15360
	s_waitcnt lgkmcnt(0)
	s_barrier
	global_load_dwordx4 v[56:59], v[128:129], off offset:384
	global_load_dwordx4 v[60:63], v[130:131], off offset:384
	global_load_dwordx4 v[44:47], v[132:133], off offset:384
	global_load_dwordx4 v[48:51], v[134:135], off offset:384
	global_load_dwordx4 v[52:55], v[136:137], off offset:384
	global_load_dwordx4 v[32:35], v[138:139], off offset:384
	global_load_dwordx4 v[36:39], v[140:141], off offset:384
	global_load_dwordx4 v[40:43], v[142:143], off offset:384
	v_mfma_f32_16x16x32_bf16 v[182:185], v[178:181], v[244:247], v[182:185]
	v_mfma_f32_16x16x32_bf16 v[186:189], v[178:181], v[248:251], v[186:189]
	v_mfma_f32_16x16x32_bf16 v[190:193], v[178:181], v[216:219], v[190:193]
	v_mfma_f32_16x16x32_bf16 v[150:153], v[178:181], v[220:223], v[150:153]
	v_mfma_f32_16x16x32_bf16 v[178:181], v[232:235], v[244:247], v[194:197]
	v_mfma_f32_16x16x32_bf16 v[194:197], v[232:235], v[248:251], v[198:201]
	v_mfma_f32_16x16x32_bf16 v[198:201], v[232:235], v[216:219], v[202:205]
	v_mfma_f32_16x16x32_bf16 v[154:157], v[232:235], v[220:223], v[154:157]
	v_mfma_f32_16x16x32_bf16 v[202:205], v[236:239], v[244:247], v[212:215]
	v_mfma_f32_16x16x32_bf16 v[212:215], v[236:239], v[248:251], v[224:227]
	v_mfma_f32_16x16x32_bf16 v[224:227], v[236:239], v[216:219], v[228:231]
	v_mfma_f32_16x16x32_bf16 v[158:161], v[236:239], v[220:223], v[158:161]
	v_mfma_f32_16x16x32_bf16 v[166:169], v[240:243], v[244:247], v[166:169]
	v_mfma_f32_16x16x32_bf16 v[170:173], v[240:243], v[248:251], v[170:173]
	v_mfma_f32_16x16x32_bf16 v[174:177], v[240:243], v[216:219], v[174:177]
	v_mfma_f32_16x16x32_bf16 v[162:165], v[240:243], v[220:223], v[162:165]
	ds_read_b128 v[216:219], v146 offset:40960
	ds_read_b128 v[220:223], v146 offset:43520
	ds_read_b128 v[228:231], v146 offset:46080
	ds_read_b128 v[232:235], v146 offset:48640
	ds_read_b128 v[236:239], v147 offset:40960
	ds_read_b128 v[240:243], v147 offset:43520
	ds_read_b128 v[244:247], v147 offset:46080
	ds_read_b128 v[248:251], v147 offset:48640
	s_waitcnt lgkmcnt(3)
	v_mfma_f32_16x16x32_bf16 v[182:185], v[216:219], v[236:239], v[182:185]
	s_waitcnt lgkmcnt(2)
	v_mfma_f32_16x16x32_bf16 v[186:189], v[216:219], v[240:243], v[186:189]
	s_waitcnt lgkmcnt(1)
	v_mfma_f32_16x16x32_bf16 v[190:193], v[216:219], v[244:247], v[190:193]
	s_waitcnt lgkmcnt(0)
	v_mfma_f32_16x16x32_bf16 v[150:153], v[216:219], v[248:251], v[150:153]
	v_mfma_f32_16x16x32_bf16 v[178:181], v[220:223], v[236:239], v[178:181]
	v_mfma_f32_16x16x32_bf16 v[194:197], v[220:223], v[240:243], v[194:197]
	v_mfma_f32_16x16x32_bf16 v[198:201], v[220:223], v[244:247], v[198:201]
	v_mfma_f32_16x16x32_bf16 v[154:157], v[220:223], v[248:251], v[154:157]
	v_mfma_f32_16x16x32_bf16 v[202:205], v[228:231], v[236:239], v[202:205]
	v_mfma_f32_16x16x32_bf16 v[212:215], v[228:231], v[240:243], v[212:215]
	v_mfma_f32_16x16x32_bf16 v[216:219], v[228:231], v[244:247], v[224:227]
	v_mfma_f32_16x16x32_bf16 v[158:161], v[228:231], v[248:251], v[158:161]
	v_mfma_f32_16x16x32_bf16 v[166:169], v[232:235], v[236:239], v[166:169]
	v_mfma_f32_16x16x32_bf16 v[170:173], v[232:235], v[240:243], v[170:173]
	v_mfma_f32_16x16x32_bf16 v[174:177], v[232:235], v[244:247], v[174:177]
	v_mfma_f32_16x16x32_bf16 v[162:165], v[232:235], v[248:251], v[162:165]
	ds_read_b128 v[220:223], v146 offset:41024
	ds_read_b128 v[224:227], v146 offset:43584
	ds_read_b128 v[228:231], v146 offset:46144
	ds_read_b128 v[232:235], v146 offset:48704
	ds_read_b128 v[236:239], v147 offset:41024
	ds_read_b128 v[240:243], v147 offset:43584
	ds_read_b128 v[244:247], v147 offset:46144
	ds_read_b128 v[248:251], v147 offset:48704
	s_waitcnt vmcnt(15)
	ds_write_b128 v145, v[0:3]
	s_waitcnt vmcnt(14)
	ds_write_b128 v145, v[4:7] offset:5120
	s_waitcnt vmcnt(13)
	ds_write_b128 v145, v[8:11] offset:10240
	s_waitcnt vmcnt(12)
	ds_write_b128 v145, v[12:15] offset:15360
	s_waitcnt vmcnt(11)
	ds_write_b128 v145, v[16:19] offset:20480
	s_waitcnt vmcnt(10)
	ds_write_b128 v145, v[20:23] offset:25600
	s_waitcnt vmcnt(9)
	ds_write_b128 v145, v[24:27] offset:30720
	s_waitcnt vmcnt(8)
	ds_write_b128 v145, v[28:31] offset:35840
	s_waitcnt lgkmcnt(0)
	s_barrier
	global_load_dwordx4 v[0:3], v[128:129], off offset:512
	global_load_dwordx4 v[4:7], v[130:131], off offset:512
	global_load_dwordx4 v[8:11], v[132:133], off offset:512
	global_load_dwordx4 v[12:15], v[134:135], off offset:512
	global_load_dwordx4 v[16:19], v[136:137], off offset:512
	global_load_dwordx4 v[20:23], v[138:139], off offset:512
	global_load_dwordx4 v[24:27], v[140:141], off offset:512
	global_load_dwordx4 v[28:31], v[142:143], off offset:512
	v_mfma_f32_16x16x32_bf16 v[182:185], v[220:223], v[236:239], v[182:185]
	v_mfma_f32_16x16x32_bf16 v[186:189], v[220:223], v[240:243], v[186:189]
	v_mfma_f32_16x16x32_bf16 v[190:193], v[220:223], v[244:247], v[190:193]
	v_mfma_f32_16x16x32_bf16 v[150:153], v[220:223], v[248:251], v[150:153]
	v_mfma_f32_16x16x32_bf16 v[178:181], v[224:227], v[236:239], v[178:181]
	v_mfma_f32_16x16x32_bf16 v[194:197], v[224:227], v[240:243], v[194:197]
	v_mfma_f32_16x16x32_bf16 v[198:201], v[224:227], v[244:247], v[198:201]
	v_mfma_f32_16x16x32_bf16 v[154:157], v[224:227], v[248:251], v[154:157]
	v_mfma_f32_16x16x32_bf16 v[202:205], v[228:231], v[236:239], v[202:205]
	v_mfma_f32_16x16x32_bf16 v[212:215], v[228:231], v[240:243], v[212:215]
	v_mfma_f32_16x16x32_bf16 v[216:219], v[228:231], v[244:247], v[216:219]
	v_mfma_f32_16x16x32_bf16 v[158:161], v[228:231], v[248:251], v[158:161]
	v_mfma_f32_16x16x32_bf16 v[166:169], v[232:235], v[236:239], v[166:169]
	v_mfma_f32_16x16x32_bf16 v[170:173], v[232:235], v[240:243], v[170:173]
	v_mfma_f32_16x16x32_bf16 v[174:177], v[232:235], v[244:247], v[174:177]
	v_mfma_f32_16x16x32_bf16 v[162:165], v[232:235], v[248:251], v[162:165]
	ds_read_b128 v[220:223], v146
	ds_read_b128 v[224:227], v146 offset:2560
	ds_read_b128 v[228:231], v146 offset:5120
	ds_read_b128 v[232:235], v146 offset:7680
	ds_read_b128 v[236:239], v147
	ds_read_b128 v[240:243], v147 offset:2560
	ds_read_b128 v[244:247], v147 offset:5120
	ds_read_b128 v[248:251], v147 offset:7680
	s_waitcnt lgkmcnt(3)
	v_mfma_f32_16x16x32_bf16 v[182:185], v[220:223], v[236:239], v[182:185]
	s_waitcnt lgkmcnt(2)
	v_mfma_f32_16x16x32_bf16 v[186:189], v[220:223], v[240:243], v[186:189]
	s_waitcnt lgkmcnt(1)
	v_mfma_f32_16x16x32_bf16 v[190:193], v[220:223], v[244:247], v[190:193]
	s_waitcnt lgkmcnt(0)
	v_mfma_f32_16x16x32_bf16 v[150:153], v[220:223], v[248:251], v[150:153]
	v_mfma_f32_16x16x32_bf16 v[178:181], v[224:227], v[236:239], v[178:181]
	v_mfma_f32_16x16x32_bf16 v[194:197], v[224:227], v[240:243], v[194:197]
	v_mfma_f32_16x16x32_bf16 v[198:201], v[224:227], v[244:247], v[198:201]
	v_mfma_f32_16x16x32_bf16 v[154:157], v[224:227], v[248:251], v[154:157]
	v_mfma_f32_16x16x32_bf16 v[202:205], v[228:231], v[236:239], v[202:205]
	v_mfma_f32_16x16x32_bf16 v[212:215], v[228:231], v[240:243], v[212:215]
	v_mfma_f32_16x16x32_bf16 v[216:219], v[228:231], v[244:247], v[216:219]
	v_mfma_f32_16x16x32_bf16 v[158:161], v[228:231], v[248:251], v[158:161]
	v_mfma_f32_16x16x32_bf16 v[166:169], v[232:235], v[236:239], v[166:169]
	v_mfma_f32_16x16x32_bf16 v[170:173], v[232:235], v[240:243], v[170:173]
	v_mfma_f32_16x16x32_bf16 v[174:177], v[232:235], v[244:247], v[174:177]
	v_mfma_f32_16x16x32_bf16 v[162:165], v[232:235], v[248:251], v[162:165]
	ds_read_b128 v[220:223], v146 offset:64
	ds_read_b128 v[224:227], v146 offset:2624
	ds_read_b128 v[228:231], v146 offset:5184
	ds_read_b128 v[232:235], v146 offset:7744
	ds_read_b128 v[236:239], v147 offset:64
	ds_read_b128 v[240:243], v147 offset:2624
	ds_read_b128 v[244:247], v147 offset:5184
	ds_read_b128 v[248:251], v147 offset:7744
	s_waitcnt vmcnt(15)
	ds_write_b128 v145, v[56:59] offset:40960
	s_waitcnt vmcnt(14)
	ds_write_b128 v145, v[60:63] offset:46080
	s_waitcnt vmcnt(13)
	ds_write_b128 v145, v[44:47] offset:51200
	s_waitcnt vmcnt(12)
	ds_write_b128 v145, v[48:51] offset:56320
	s_waitcnt vmcnt(11)
	ds_write_b128 v145, v[52:55] offset:61440
	s_waitcnt vmcnt(10)
	ds_write_b128 v148, v[32:35] offset:5120
	s_waitcnt vmcnt(9)
	ds_write_b128 v148, v[36:39] offset:10240
	s_waitcnt vmcnt(8)
	ds_write_b128 v148, v[40:43] offset:15360
	s_waitcnt lgkmcnt(0)
	s_barrier
	global_load_dwordx4 v[56:59], v[128:129], off offset:640
	global_load_dwordx4 v[60:63], v[130:131], off offset:640
	global_load_dwordx4 v[44:47], v[132:133], off offset:640
	global_load_dwordx4 v[48:51], v[134:135], off offset:640
	global_load_dwordx4 v[52:55], v[136:137], off offset:640
	global_load_dwordx4 v[32:35], v[138:139], off offset:640
	global_load_dwordx4 v[36:39], v[140:141], off offset:640
	global_load_dwordx4 v[40:43], v[142:143], off offset:640
	v_mfma_f32_16x16x32_bf16 v[182:185], v[220:223], v[236:239], v[182:185]
	v_mfma_f32_16x16x32_bf16 v[186:189], v[220:223], v[240:243], v[186:189]
	v_mfma_f32_16x16x32_bf16 v[190:193], v[220:223], v[244:247], v[190:193]
	v_mfma_f32_16x16x32_bf16 v[150:153], v[220:223], v[248:251], v[150:153]
	v_mfma_f32_16x16x32_bf16 v[178:181], v[224:227], v[236:239], v[178:181]
	v_mfma_f32_16x16x32_bf16 v[194:197], v[224:227], v[240:243], v[194:197]
	v_mfma_f32_16x16x32_bf16 v[198:201], v[224:227], v[244:247], v[198:201]
	v_mfma_f32_16x16x32_bf16 v[154:157], v[224:227], v[248:251], v[154:157]
	v_mfma_f32_16x16x32_bf16 v[202:205], v[228:231], v[236:239], v[202:205]
	v_mfma_f32_16x16x32_bf16 v[212:215], v[228:231], v[240:243], v[212:215]
	v_mfma_f32_16x16x32_bf16 v[216:219], v[228:231], v[244:247], v[216:219]
	v_mfma_f32_16x16x32_bf16 v[158:161], v[228:231], v[248:251], v[158:161]
	v_mfma_f32_16x16x32_bf16 v[166:169], v[232:235], v[236:239], v[166:169]
	v_mfma_f32_16x16x32_bf16 v[170:173], v[232:235], v[240:243], v[170:173]
	v_mfma_f32_16x16x32_bf16 v[174:177], v[232:235], v[244:247], v[174:177]
	v_mfma_f32_16x16x32_bf16 v[162:165], v[232:235], v[248:251], v[162:165]
	ds_read_b128 v[220:223], v146 offset:40960
	ds_read_b128 v[224:227], v146 offset:43520
	ds_read_b128 v[228:231], v146 offset:46080
	ds_read_b128 v[232:235], v146 offset:48640
	ds_read_b128 v[236:239], v147 offset:40960
	ds_read_b128 v[240:243], v147 offset:43520
	ds_read_b128 v[244:247], v147 offset:46080
	ds_read_b128 v[248:251], v147 offset:48640
	s_waitcnt lgkmcnt(3)
	v_mfma_f32_16x16x32_bf16 v[182:185], v[220:223], v[236:239], v[182:185]
	s_waitcnt lgkmcnt(2)
	v_mfma_f32_16x16x32_bf16 v[186:189], v[220:223], v[240:243], v[186:189]
	s_waitcnt lgkmcnt(1)
	v_mfma_f32_16x16x32_bf16 v[190:193], v[220:223], v[244:247], v[190:193]
	s_waitcnt lgkmcnt(0)
	v_mfma_f32_16x16x32_bf16 v[150:153], v[220:223], v[248:251], v[150:153]
	v_mfma_f32_16x16x32_bf16 v[178:181], v[224:227], v[236:239], v[178:181]
	v_mfma_f32_16x16x32_bf16 v[194:197], v[224:227], v[240:243], v[194:197]
	v_mfma_f32_16x16x32_bf16 v[198:201], v[224:227], v[244:247], v[198:201]
	v_mfma_f32_16x16x32_bf16 v[154:157], v[224:227], v[248:251], v[154:157]
	v_mfma_f32_16x16x32_bf16 v[202:205], v[228:231], v[236:239], v[202:205]
	v_mfma_f32_16x16x32_bf16 v[212:215], v[228:231], v[240:243], v[212:215]
	v_mfma_f32_16x16x32_bf16 v[216:219], v[228:231], v[244:247], v[216:219]
	v_mfma_f32_16x16x32_bf16 v[158:161], v[228:231], v[248:251], v[158:161]
	v_mfma_f32_16x16x32_bf16 v[166:169], v[232:235], v[236:239], v[166:169]
	v_mfma_f32_16x16x32_bf16 v[170:173], v[232:235], v[240:243], v[170:173]
	v_mfma_f32_16x16x32_bf16 v[174:177], v[232:235], v[244:247], v[174:177]
	v_mfma_f32_16x16x32_bf16 v[162:165], v[232:235], v[248:251], v[162:165]
	ds_read_b128 v[220:223], v146 offset:41024
	ds_read_b128 v[224:227], v146 offset:43584
	ds_read_b128 v[228:231], v146 offset:46144
	ds_read_b128 v[232:235], v146 offset:48704
	ds_read_b128 v[236:239], v147 offset:41024
	ds_read_b128 v[240:243], v147 offset:43584
	ds_read_b128 v[244:247], v147 offset:46144
	ds_read_b128 v[248:251], v147 offset:48704
	s_waitcnt vmcnt(15)
	ds_write_b128 v145, v[0:3]
	s_waitcnt vmcnt(14)
	ds_write_b128 v145, v[4:7] offset:5120
	s_waitcnt vmcnt(13)
	ds_write_b128 v145, v[8:11] offset:10240
	s_waitcnt vmcnt(12)
	ds_write_b128 v145, v[12:15] offset:15360
	s_waitcnt vmcnt(11)
	ds_write_b128 v145, v[16:19] offset:20480
	s_waitcnt vmcnt(10)
	ds_write_b128 v145, v[20:23] offset:25600
	s_waitcnt vmcnt(9)
	ds_write_b128 v145, v[24:27] offset:30720
	s_waitcnt vmcnt(8)
	ds_write_b128 v145, v[28:31] offset:35840
	s_waitcnt lgkmcnt(0)
	s_barrier
	global_load_dwordx4 v[0:3], v[128:129], off offset:768
	global_load_dwordx4 v[4:7], v[130:131], off offset:768
	global_load_dwordx4 v[8:11], v[132:133], off offset:768
	global_load_dwordx4 v[12:15], v[134:135], off offset:768
	global_load_dwordx4 v[16:19], v[136:137], off offset:768
	global_load_dwordx4 v[20:23], v[138:139], off offset:768
	global_load_dwordx4 v[24:27], v[140:141], off offset:768
	global_load_dwordx4 v[28:31], v[142:143], off offset:768
	v_mfma_f32_16x16x32_bf16 v[182:185], v[220:223], v[236:239], v[182:185]
	v_mfma_f32_16x16x32_bf16 v[186:189], v[220:223], v[240:243], v[186:189]
	v_mfma_f32_16x16x32_bf16 v[190:193], v[220:223], v[244:247], v[190:193]
	v_mfma_f32_16x16x32_bf16 v[150:153], v[220:223], v[248:251], v[150:153]
	v_mfma_f32_16x16x32_bf16 v[178:181], v[224:227], v[236:239], v[178:181]
	v_mfma_f32_16x16x32_bf16 v[194:197], v[224:227], v[240:243], v[194:197]
	v_mfma_f32_16x16x32_bf16 v[198:201], v[224:227], v[244:247], v[198:201]
	v_mfma_f32_16x16x32_bf16 v[154:157], v[224:227], v[248:251], v[154:157]
	v_mfma_f32_16x16x32_bf16 v[202:205], v[228:231], v[236:239], v[202:205]
	v_mfma_f32_16x16x32_bf16 v[212:215], v[228:231], v[240:243], v[212:215]
	v_mfma_f32_16x16x32_bf16 v[216:219], v[228:231], v[244:247], v[216:219]
	v_mfma_f32_16x16x32_bf16 v[158:161], v[228:231], v[248:251], v[158:161]
	v_mfma_f32_16x16x32_bf16 v[166:169], v[232:235], v[236:239], v[166:169]
	v_mfma_f32_16x16x32_bf16 v[170:173], v[232:235], v[240:243], v[170:173]
	v_mfma_f32_16x16x32_bf16 v[174:177], v[232:235], v[244:247], v[174:177]
	v_mfma_f32_16x16x32_bf16 v[162:165], v[232:235], v[248:251], v[162:165]
	ds_read_b128 v[220:223], v146
	ds_read_b128 v[224:227], v146 offset:2560
	ds_read_b128 v[228:231], v146 offset:5120
	ds_read_b128 v[232:235], v146 offset:7680
	ds_read_b128 v[236:239], v147
	ds_read_b128 v[240:243], v147 offset:2560
	ds_read_b128 v[244:247], v147 offset:5120
	ds_read_b128 v[248:251], v147 offset:7680
	s_waitcnt lgkmcnt(3)
	v_mfma_f32_16x16x32_bf16 v[182:185], v[220:223], v[236:239], v[182:185]
	s_waitcnt lgkmcnt(2)
	v_mfma_f32_16x16x32_bf16 v[186:189], v[220:223], v[240:243], v[186:189]
	s_waitcnt lgkmcnt(1)
	v_mfma_f32_16x16x32_bf16 v[190:193], v[220:223], v[244:247], v[190:193]
	s_waitcnt lgkmcnt(0)
	v_mfma_f32_16x16x32_bf16 v[150:153], v[220:223], v[248:251], v[150:153]
	v_mfma_f32_16x16x32_bf16 v[178:181], v[224:227], v[236:239], v[178:181]
	v_mfma_f32_16x16x32_bf16 v[194:197], v[224:227], v[240:243], v[194:197]
	v_mfma_f32_16x16x32_bf16 v[198:201], v[224:227], v[244:247], v[198:201]
	v_mfma_f32_16x16x32_bf16 v[154:157], v[224:227], v[248:251], v[154:157]
	v_mfma_f32_16x16x32_bf16 v[202:205], v[228:231], v[236:239], v[202:205]
	v_mfma_f32_16x16x32_bf16 v[212:215], v[228:231], v[240:243], v[212:215]
	v_mfma_f32_16x16x32_bf16 v[216:219], v[228:231], v[244:247], v[216:219]
	v_mfma_f32_16x16x32_bf16 v[158:161], v[228:231], v[248:251], v[158:161]
	v_mfma_f32_16x16x32_bf16 v[166:169], v[232:235], v[236:239], v[166:169]
	v_mfma_f32_16x16x32_bf16 v[170:173], v[232:235], v[240:243], v[170:173]
	v_mfma_f32_16x16x32_bf16 v[174:177], v[232:235], v[244:247], v[174:177]
	v_mfma_f32_16x16x32_bf16 v[162:165], v[232:235], v[248:251], v[162:165]
	ds_read_b128 v[220:223], v146 offset:64
	ds_read_b128 v[224:227], v146 offset:2624
	ds_read_b128 v[228:231], v146 offset:5184
	ds_read_b128 v[232:235], v146 offset:7744
	ds_read_b128 v[236:239], v147 offset:64
	ds_read_b128 v[240:243], v147 offset:2624
	ds_read_b128 v[244:247], v147 offset:5184
	ds_read_b128 v[248:251], v147 offset:7744
	s_waitcnt vmcnt(15)
	ds_write_b128 v145, v[56:59] offset:40960
	s_waitcnt vmcnt(14)
	ds_write_b128 v145, v[60:63] offset:46080
	s_waitcnt vmcnt(13)
	ds_write_b128 v145, v[44:47] offset:51200
	s_waitcnt vmcnt(12)
	ds_write_b128 v145, v[48:51] offset:56320
	s_waitcnt vmcnt(11)
	ds_write_b128 v145, v[52:55] offset:61440
	s_waitcnt vmcnt(10)
	ds_write_b128 v148, v[32:35] offset:5120
	s_waitcnt vmcnt(9)
	ds_write_b128 v148, v[36:39] offset:10240
	s_waitcnt vmcnt(8)
	ds_write_b128 v148, v[40:43] offset:15360
	s_waitcnt lgkmcnt(0)
	s_barrier
	global_load_dwordx4 v[56:59], v[128:129], off offset:896
	global_load_dwordx4 v[60:63], v[130:131], off offset:896
	global_load_dwordx4 v[44:47], v[132:133], off offset:896
	global_load_dwordx4 v[48:51], v[134:135], off offset:896
	global_load_dwordx4 v[52:55], v[136:137], off offset:896
	global_load_dwordx4 v[32:35], v[138:139], off offset:896
	global_load_dwordx4 v[36:39], v[140:141], off offset:896
	global_load_dwordx4 v[40:43], v[142:143], off offset:896
	v_mfma_f32_16x16x32_bf16 v[182:185], v[220:223], v[236:239], v[182:185]
	v_mfma_f32_16x16x32_bf16 v[186:189], v[220:223], v[240:243], v[186:189]
	v_mfma_f32_16x16x32_bf16 v[190:193], v[220:223], v[244:247], v[190:193]
	v_mfma_f32_16x16x32_bf16 v[150:153], v[220:223], v[248:251], v[150:153]
	v_mfma_f32_16x16x32_bf16 v[178:181], v[224:227], v[236:239], v[178:181]
	v_mfma_f32_16x16x32_bf16 v[194:197], v[224:227], v[240:243], v[194:197]
	v_mfma_f32_16x16x32_bf16 v[198:201], v[224:227], v[244:247], v[198:201]
	v_mfma_f32_16x16x32_bf16 v[154:157], v[224:227], v[248:251], v[154:157]
	v_mfma_f32_16x16x32_bf16 v[202:205], v[228:231], v[236:239], v[202:205]
	v_mfma_f32_16x16x32_bf16 v[212:215], v[228:231], v[240:243], v[212:215]
	v_mfma_f32_16x16x32_bf16 v[216:219], v[228:231], v[244:247], v[216:219]
	v_mfma_f32_16x16x32_bf16 v[158:161], v[228:231], v[248:251], v[158:161]
	v_mfma_f32_16x16x32_bf16 v[166:169], v[232:235], v[236:239], v[166:169]
	v_mfma_f32_16x16x32_bf16 v[170:173], v[232:235], v[240:243], v[170:173]
	v_mfma_f32_16x16x32_bf16 v[174:177], v[232:235], v[244:247], v[174:177]
	v_mfma_f32_16x16x32_bf16 v[162:165], v[232:235], v[248:251], v[162:165]
	ds_read_b128 v[128:131], v146 offset:40960
	ds_read_b128 v[132:135], v146 offset:43520
	ds_read_b128 v[136:139], v146 offset:46080
	ds_read_b128 v[140:143], v146 offset:48640
	ds_read_b128 v[220:223], v147 offset:40960
	ds_read_b128 v[224:227], v147 offset:43520
	ds_read_b128 v[228:231], v147 offset:46080
	ds_read_b128 v[232:235], v147 offset:48640
	s_waitcnt lgkmcnt(3)
	v_mfma_f32_16x16x32_bf16 v[182:185], v[128:131], v[220:223], v[182:185]
	s_waitcnt lgkmcnt(2)
	v_mfma_f32_16x16x32_bf16 v[186:189], v[128:131], v[224:227], v[186:189]
	s_waitcnt lgkmcnt(1)
	v_mfma_f32_16x16x32_bf16 v[190:193], v[128:131], v[228:231], v[190:193]
	s_waitcnt lgkmcnt(0)
	v_mfma_f32_16x16x32_bf16 v[128:131], v[128:131], v[232:235], v[150:153]
	v_mfma_f32_16x16x32_bf16 v[150:153], v[132:135], v[220:223], v[178:181]
	v_mfma_f32_16x16x32_bf16 v[178:181], v[132:135], v[224:227], v[194:197]
	v_mfma_f32_16x16x32_bf16 v[194:197], v[132:135], v[228:231], v[198:201]
	v_mfma_f32_16x16x32_bf16 v[132:135], v[132:135], v[232:235], v[154:157]
	v_mfma_f32_16x16x32_bf16 v[154:157], v[136:139], v[220:223], v[202:205]
	v_mfma_f32_16x16x32_bf16 v[198:201], v[136:139], v[224:227], v[212:215]
	v_mfma_f32_16x16x32_bf16 v[202:205], v[136:139], v[228:231], v[216:219]
	v_mfma_f32_16x16x32_bf16 v[136:139], v[136:139], v[232:235], v[158:161]
	v_mfma_f32_16x16x32_bf16 v[158:161], v[140:143], v[220:223], v[166:169]
	v_mfma_f32_16x16x32_bf16 v[166:169], v[140:143], v[224:227], v[170:173]
	v_mfma_f32_16x16x32_bf16 v[170:173], v[140:143], v[228:231], v[174:177]
	v_mfma_f32_16x16x32_bf16 v[140:143], v[140:143], v[232:235], v[162:165]
	s_nop 2
	ds_read_b128 v[162:165], v146 offset:41024
	ds_read_b128 v[174:177], v146 offset:43584
	ds_read_b128 v[212:215], v146 offset:46144
	ds_read_b128 v[216:219], v146 offset:48704
	ds_read_b128 v[220:223], v147 offset:41024
	ds_read_b128 v[224:227], v147 offset:43584
	ds_read_b128 v[228:231], v147 offset:46144
	ds_read_b128 v[232:235], v147 offset:48704
	s_waitcnt vmcnt(15)
	ds_write_b128 v145, v[0:3]
	s_waitcnt vmcnt(14)
	ds_write_b128 v145, v[4:7] offset:5120
	s_waitcnt vmcnt(13)
	ds_write_b128 v145, v[8:11] offset:10240
	s_waitcnt vmcnt(12)
	ds_write_b128 v145, v[12:15] offset:15360
	s_waitcnt vmcnt(11)
	ds_write_b128 v145, v[16:19] offset:20480
	s_waitcnt vmcnt(10)
	ds_write_b128 v145, v[20:23] offset:25600
	s_waitcnt vmcnt(9)
	ds_write_b128 v145, v[24:27] offset:30720
	s_waitcnt vmcnt(8)
	ds_write_b128 v145, v[28:31] offset:35840
	s_waitcnt lgkmcnt(0)
	s_barrier
	ds_read_b128 v[0:3], v146
	ds_read_b128 v[4:7], v146 offset:2560
	ds_read_b128 v[8:11], v146 offset:5120
	ds_read_b128 v[12:15], v146 offset:7680
	ds_read_b128 v[16:19], v147
	ds_read_b128 v[20:23], v147 offset:2560
	ds_read_b128 v[24:27], v147 offset:5120
	ds_read_b128 v[28:31], v147 offset:7680
	v_mfma_f32_16x16x32_bf16 v[182:185], v[162:165], v[220:223], v[182:185]
	v_mfma_f32_16x16x32_bf16 v[186:189], v[162:165], v[224:227], v[186:189]
	v_mfma_f32_16x16x32_bf16 v[190:193], v[162:165], v[228:231], v[190:193]
	v_mfma_f32_16x16x32_bf16 v[128:131], v[162:165], v[232:235], v[128:131]
	v_mfma_f32_16x16x32_bf16 v[150:153], v[174:177], v[220:223], v[150:153]
	v_mfma_f32_16x16x32_bf16 v[162:165], v[174:177], v[224:227], v[178:181]
	v_mfma_f32_16x16x32_bf16 v[178:181], v[174:177], v[228:231], v[194:197]
	v_mfma_f32_16x16x32_bf16 v[132:135], v[174:177], v[232:235], v[132:135]
	v_mfma_f32_16x16x32_bf16 v[154:157], v[212:215], v[220:223], v[154:157]
	v_mfma_f32_16x16x32_bf16 v[174:177], v[212:215], v[224:227], v[198:201]
	v_mfma_f32_16x16x32_bf16 v[194:197], v[212:215], v[228:231], v[202:205]
	v_mfma_f32_16x16x32_bf16 v[136:139], v[212:215], v[232:235], v[136:139]
	v_mfma_f32_16x16x32_bf16 v[158:161], v[216:219], v[220:223], v[158:161]
	v_mfma_f32_16x16x32_bf16 v[166:169], v[216:219], v[224:227], v[166:169]
	v_mfma_f32_16x16x32_bf16 v[170:173], v[216:219], v[228:231], v[170:173]
	v_mfma_f32_16x16x32_bf16 v[140:143], v[216:219], v[232:235], v[140:143]
	s_waitcnt lgkmcnt(3)
	v_mfma_f32_16x16x32_bf16 v[182:185], v[0:3], v[16:19], v[182:185]
	s_waitcnt lgkmcnt(2)
	v_mfma_f32_16x16x32_bf16 v[186:189], v[0:3], v[20:23], v[186:189]
	s_waitcnt lgkmcnt(1)
	v_mfma_f32_16x16x32_bf16 v[190:193], v[0:3], v[24:27], v[190:193]
	s_waitcnt lgkmcnt(0)
	v_mfma_f32_16x16x32_bf16 v[0:3], v[0:3], v[28:31], v[128:131]
	v_mfma_f32_16x16x32_bf16 v[128:131], v[4:7], v[16:19], v[150:153]
	v_mfma_f32_16x16x32_bf16 v[150:153], v[4:7], v[20:23], v[162:165]
	v_mfma_f32_16x16x32_bf16 v[162:165], v[4:7], v[24:27], v[178:181]
	v_mfma_f32_16x16x32_bf16 v[4:7], v[4:7], v[28:31], v[132:135]
	v_mfma_f32_16x16x32_bf16 v[132:135], v[8:11], v[16:19], v[154:157]
	v_mfma_f32_16x16x32_bf16 v[154:157], v[8:11], v[20:23], v[174:177]
	v_mfma_f32_16x16x32_bf16 v[174:177], v[8:11], v[24:27], v[194:197]
	v_mfma_f32_16x16x32_bf16 v[8:11], v[8:11], v[28:31], v[136:139]
	v_mfma_f32_16x16x32_bf16 v[16:19], v[12:15], v[16:19], v[158:161]
	v_mfma_f32_16x16x32_bf16 v[20:23], v[12:15], v[20:23], v[166:169]
	v_mfma_f32_16x16x32_bf16 v[24:27], v[12:15], v[24:27], v[170:173]
	v_mfma_f32_16x16x32_bf16 v[12:15], v[12:15], v[28:31], v[140:143]
	ds_read_b128 v[28:31], v146 offset:64
	ds_read_b128 v[136:139], v146 offset:2624
	s_nop 0
	ds_read_b128 v[140:143], v146 offset:5184
	ds_read_b128 v[158:161], v146 offset:7744
	ds_read_b128 v[166:169], v147 offset:64
	ds_read_b128 v[170:173], v147 offset:2624
	ds_read_b128 v[178:181], v147 offset:5184
	ds_read_b128 v[194:197], v147 offset:7744
	s_waitcnt vmcnt(7)
	ds_write_b128 v145, v[56:59] offset:40960
	s_waitcnt vmcnt(6)
	ds_write_b128 v145, v[60:63] offset:46080
	s_waitcnt vmcnt(5)
	ds_write_b128 v145, v[44:47] offset:51200
	s_waitcnt vmcnt(4)
	ds_write_b128 v145, v[48:51] offset:56320
	s_waitcnt vmcnt(3)
	ds_write_b128 v145, v[52:55] offset:61440
	s_waitcnt vmcnt(2)
	ds_write_b128 v148, v[32:35] offset:5120
	s_waitcnt vmcnt(1)
	ds_write_b128 v148, v[36:39] offset:10240
	s_waitcnt vmcnt(0)
	ds_write_b128 v148, v[40:43] offset:15360
	s_waitcnt lgkmcnt(0)
	s_barrier
	ds_read_b128 v[32:35], v146 offset:40960
	ds_read_b128 v[36:39], v146 offset:43520
	ds_read_b128 v[40:43], v146 offset:46080
	ds_read_b128 v[44:47], v146 offset:48640
	ds_read_b128 v[48:51], v147 offset:40960
	ds_read_b128 v[52:55], v147 offset:43520
	ds_read_b128 v[56:59], v147 offset:46080
	ds_read_b128 v[60:63], v147 offset:48640
	v_mfma_f32_16x16x32_bf16 v[182:185], v[28:31], v[166:169], v[182:185]
	v_mfma_f32_16x16x32_bf16 v[186:189], v[28:31], v[170:173], v[186:189]
	v_mfma_f32_16x16x32_bf16 v[190:193], v[28:31], v[178:181], v[190:193]
	v_mfma_f32_16x16x32_bf16 v[0:3], v[28:31], v[194:197], v[0:3]
	v_mfma_f32_16x16x32_bf16 v[28:31], v[136:139], v[166:169], v[128:131]
	v_mfma_f32_16x16x32_bf16 v[128:131], v[136:139], v[170:173], v[150:153]
	v_mfma_f32_16x16x32_bf16 v[150:153], v[136:139], v[178:181], v[162:165]
	v_mfma_f32_16x16x32_bf16 v[4:7], v[136:139], v[194:197], v[4:7]
	v_mfma_f32_16x16x32_bf16 v[132:135], v[140:143], v[166:169], v[132:135]
	v_mfma_f32_16x16x32_bf16 v[136:139], v[140:143], v[170:173], v[154:157]
	v_mfma_f32_16x16x32_bf16 v[154:157], v[140:143], v[178:181], v[174:177]
	v_mfma_f32_16x16x32_bf16 v[8:11], v[140:143], v[194:197], v[8:11]
	v_mfma_f32_16x16x32_bf16 v[16:19], v[158:161], v[166:169], v[16:19]
	v_mfma_f32_16x16x32_bf16 v[20:23], v[158:161], v[170:173], v[20:23]
	v_mfma_f32_16x16x32_bf16 v[24:27], v[158:161], v[178:181], v[24:27]
	v_mfma_f32_16x16x32_bf16 v[12:15], v[158:161], v[194:197], v[12:15]
	s_waitcnt lgkmcnt(3)
	v_mfma_f32_16x16x32_bf16 v[140:143], v[32:35], v[48:51], v[182:185]
	s_waitcnt lgkmcnt(2)
	v_mfma_f32_16x16x32_bf16 v[158:161], v[32:35], v[52:55], v[186:189]
	s_waitcnt lgkmcnt(1)
	v_mfma_f32_16x16x32_bf16 v[162:165], v[32:35], v[56:59], v[190:193]
	s_waitcnt lgkmcnt(0)
	v_mfma_f32_16x16x32_bf16 v[0:3], v[32:35], v[60:63], v[0:3]
	v_mfma_f32_16x16x32_bf16 v[28:31], v[36:39], v[48:51], v[28:31]
	v_mfma_f32_16x16x32_bf16 v[32:35], v[36:39], v[52:55], v[128:131]
	v_mfma_f32_16x16x32_bf16 v[128:131], v[36:39], v[56:59], v[150:153]
	v_mfma_f32_16x16x32_bf16 v[4:7], v[36:39], v[60:63], v[4:7]
	v_mfma_f32_16x16x32_bf16 v[36:39], v[40:43], v[48:51], v[132:135]
	v_mfma_f32_16x16x32_bf16 v[132:135], v[40:43], v[52:55], v[136:139]
	v_mfma_f32_16x16x32_bf16 v[136:139], v[40:43], v[56:59], v[154:157]
	v_mfma_f32_16x16x32_bf16 v[8:11], v[40:43], v[60:63], v[8:11]
	v_mfma_f32_16x16x32_bf16 v[16:19], v[44:47], v[48:51], v[16:19]
	v_mfma_f32_16x16x32_bf16 v[20:23], v[44:47], v[52:55], v[20:23]
	v_mfma_f32_16x16x32_bf16 v[24:27], v[44:47], v[56:59], v[24:27]
	v_mfma_f32_16x16x32_bf16 v[12:15], v[44:47], v[60:63], v[12:15]
	ds_read_b128 v[40:43], v146 offset:41024
	ds_read_b128 v[44:47], v146 offset:43584
	ds_read_b128 v[48:51], v146 offset:46144
	ds_read_b128 v[52:55], v146 offset:48704
	ds_read_b128 v[56:59], v147 offset:41024
	ds_read_b128 v[60:63], v147 offset:43584
	ds_read_b128 v[148:151], v147 offset:46144
	ds_read_b128 v[152:155], v147 offset:48704
	s_waitcnt lgkmcnt(0)
	s_barrier
	v_mfma_f32_16x16x32_bf16 v[140:143], v[40:43], v[56:59], v[140:143]
	v_mfma_f32_16x16x32_bf16 v[156:159], v[40:43], v[60:63], v[158:161]
	v_mfma_f32_16x16x32_bf16 v[160:163], v[40:43], v[148:151], v[162:165]
	v_mfma_f32_16x16x32_bf16 v[0:3], v[40:43], v[152:155], v[0:3]
	v_mfma_f32_16x16x32_bf16 v[28:31], v[44:47], v[56:59], v[28:31]
	v_mfma_f32_16x16x32_bf16 v[32:35], v[44:47], v[60:63], v[32:35]
	v_mfma_f32_16x16x32_bf16 v[40:43], v[44:47], v[148:151], v[128:131]
	v_mfma_f32_16x16x32_bf16 v[4:7], v[44:47], v[152:155], v[4:7]
	v_mfma_f32_16x16x32_bf16 v[36:39], v[48:51], v[56:59], v[36:39]
	v_mfma_f32_16x16x32_bf16 v[44:47], v[48:51], v[60:63], v[132:135]
	v_mfma_f32_16x16x32_bf16 v[128:131], v[48:51], v[148:151], v[136:139]
	v_mfma_f32_16x16x32_bf16 v[8:11], v[48:51], v[152:155], v[8:11]
	v_mov_b32_e32 v48, v211
	s_nop 0
	v_lshrrev_b32_e32 v50, 2, v48
	v_lshrrev_b32_e32 v49, 1, v48
	v_and_b32_e32 v50, 12, v50
	v_and_or_b32 v49, v49, s43, v50
	v_and_b32_e32 v48, 0x4f, v48
	v_lshlrev_b32_e32 v48, 2, v48
	v_mul_lo_u32 v49, v49, s22
	v_add3_u32 v48, 0, v48, v49
	v_mfma_f32_16x16x32_bf16 v[16:19], v[52:55], v[56:59], v[16:19]
	v_add_u32_e32 v49, 0x400, v48
	ds_write2_b32 v48, v140, v156 offset1:16
	ds_write2_b32 v48, v141, v157 offset0:132 offset1:148
	ds_write2_b32 v49, v142, v158 offset0:8 offset1:24
	ds_write2_b32 v49, v143, v159 offset0:140 offset1:156
	ds_write2_b32 v48, v160, v0 offset0:32 offset1:48
	ds_write2_b32 v48, v161, v1 offset0:164 offset1:180
	ds_write2_b32 v49, v162, v2 offset0:40 offset1:56
	ds_write2_b32 v49, v163, v3 offset0:172 offset1:188
	v_mfma_f32_16x16x32_bf16 v[20:23], v[52:55], v[60:63], v[20:23]
	v_add_u32_e32 v0, 0x2000, v48
	v_add_u32_e32 v1, 0x2400, v48
	ds_write2_b32 v0, v28, v32 offset0:64 offset1:80
	ds_write2_b32 v0, v29, v33 offset0:196 offset1:212
	v_mfma_f32_16x16x32_bf16 v[24:27], v[52:55], v[148:151], v[24:27]
	ds_write2_b32 v1, v30, v34 offset0:72 offset1:88
	ds_write2_b32 v1, v31, v35 offset0:204 offset1:220
	ds_write2_b32 v0, v40, v4 offset0:96 offset1:112
	ds_write2_b32 v0, v41, v5 offset0:228 offset1:244
	ds_write2_b32 v1, v42, v6 offset0:104 offset1:120
	ds_write2_b32 v1, v43, v7 offset0:236 offset1:252
	v_add_u32_e32 v0, 0x4000, v48
	v_add_u32_e32 v1, 0x4400, v48
	v_mfma_f32_16x16x32_bf16 v[12:15], v[52:55], v[152:155], v[12:15]
	v_add_u32_e32 v2, 0x4800, v48
	ds_write2_b32 v0, v36, v44 offset0:128 offset1:144
	ds_write2_b32 v1, v37, v45 offset0:4 offset1:20
	ds_write2_b32 v1, v38, v46 offset0:136 offset1:152
	ds_write2_b32 v2, v39, v47 offset0:12 offset1:28
	ds_write2_b32 v0, v128, v8 offset0:160 offset1:176
	ds_write2_b32 v1, v129, v9 offset0:36 offset1:52
	ds_write2_b32 v1, v130, v10 offset0:168 offset1:184
	ds_write2_b32 v2, v131, v11 offset0:44 offset1:60
	v_add_u32_e32 v0, 0x6000, v48
	v_add_u32_e32 v1, 0x6400, v48
	v_add_u32_e32 v2, 0x6800, v48
	ds_write2_b32 v0, v16, v20 offset0:192 offset1:208
	ds_write2_b32 v1, v17, v21 offset0:68 offset1:84
	ds_write2_b32 v1, v18, v22 offset0:200 offset1:216
	ds_write2_b32 v2, v19, v23 offset0:76 offset1:92
	ds_write2_b32 v0, v24, v12 offset0:224 offset1:240
	ds_write2_b32 v1, v25, v13 offset0:100 offset1:116
	ds_write2_b32 v1, v26, v14 offset0:232 offset1:248
	ds_write2_b32 v2, v27, v15 offset0:108 offset1:124
	v_mov_b32_e32 v0, v211
	s_waitcnt lgkmcnt(0)
	s_barrier
	s_nop 0
	v_ashrrev_i32_e32 v8, 4, v0
	v_lshlrev_b32_e32 v1, 5, v0
	v_and_b32_e32 v11, 15, v0
	v_and_b32_e32 v9, 0x1e0, v1
	v_lshlrev_b32_e32 v4, 5, v11
	v_mul_lo_u32 v10, v8, s22
	global_load_dwordx4 v[0:3], v4, s[20:21] offset:16
	s_nop 0
	global_load_dwordx4 v[4:7], v4, s[20:21]
	v_add3_u32 v10, 0, v9, v10
	v_mad_i64_i32 v[8:9], s[20:21], v8, s39, 0
	s_add_u32 s20, s2, s19
	v_lshl_or_b32 v8, v11, 4, v8
	s_addc_u32 s21, s3, s16
	v_lshl_add_u64 v[8:9], s[20:21], 0, v[8:9]
	s_mov_b32 s20, 0xcc01000
	v_add_co_u32_e32 v12, vcc, s20, v8
	s_add_u32 s6, s6, 0x1000
	s_nop 0
	v_addc_co_u32_e32 v13, vcc, 0, v9, vcc
	global_load_dwordx4 v[12:15], v[12:13], off offset:2048
	s_mov_b32 s20, 0xcc31000
	v_add_co_u32_e32 v32, vcc, s20, v8
	s_nop 1
	v_addc_co_u32_e32 v33, vcc, 0, v9, vcc
	global_load_dwordx4 v[32:35], v[32:33], off offset:2048
	s_mov_b32 s20, 0xcc61000
	v_add_co_u32_e32 v36, vcc, s20, v8
	s_nop 1
	v_addc_co_u32_e32 v37, vcc, 0, v9, vcc
	global_load_dwordx4 v[36:39], v[36:37], off offset:2048
	s_mov_b32 s20, 0xcc91000
	v_add_co_u32_e32 v40, vcc, s20, v8
	s_nop 1
	v_addc_co_u32_e32 v41, vcc, 0, v9, vcc
	global_load_dwordx4 v[40:43], v[40:41], off offset:2048
	s_mov_b32 s20, 0xccc1000
	v_add_co_u32_e32 v44, vcc, s20, v8
	s_nop 1
	v_addc_co_u32_e32 v45, vcc, 0, v9, vcc
	global_load_dwordx4 v[44:47], v[44:45], off offset:2048
	s_mov_b32 s20, 0xccf1000
	v_add_co_u32_e32 v48, vcc, s20, v8
	s_nop 1
	v_addc_co_u32_e32 v49, vcc, 0, v9, vcc
	global_load_dwordx4 v[48:51], v[48:49], off offset:2048
	s_mov_b32 s20, 0xcd21000
	v_add_co_u32_e32 v52, vcc, s20, v8
	s_nop 1
	v_addc_co_u32_e32 v53, vcc, 0, v9, vcc
	global_load_dwordx4 v[52:55], v[52:53], off offset:2048
	s_mov_b32 s20, 0xcd51000
	v_add_co_u32_e32 v56, vcc, s20, v8
	s_nop 1
	v_addc_co_u32_e32 v57, vcc, 0, v9, vcc
	global_load_dwordx4 v[56:59], v[56:57], off offset:2048
	s_addc_u32 s7, s7, 0
	s_add_u32 s19, s19, 0x800
	s_addc_u32 s16, s16, 0
	s_add_u32 s15, s15, 0x400
	s_addc_u32 s13, s13, 0
	s_add_u32 s8, s8, 0x100000
	s_addc_u32 s9, s9, 0
	s_cmpk_eq_i32 s6, 0x3000
	s_waitcnt vmcnt(7)
	v_lshlrev_b32_e32 v11, 16, v12
	v_add_f32_e32 v11, v4, v11
	v_and_b32_e32 v12, 0xffff0000, v12
	v_mul_f32_e32 v11, 0xbfb8aa3b, v11
	v_exp_f32_e32 v20, v11
	v_add_f32_e32 v11, v5, v12
	v_mul_f32_e32 v11, 0xbfb8aa3b, v11
	v_exp_f32_e32 v21, v11
	v_lshlrev_b32_e32 v22, 16, v13
	v_and_b32_e32 v23, 0xffff0000, v13
	v_lshlrev_b32_e32 v24, 16, v14
	v_and_b32_e32 v25, 0xffff0000, v14
	v_lshlrev_b32_e32 v26, 16, v15
	v_and_b32_e32 v27, 0xffff0000, v15
	ds_read_b128 v[12:15], v10
	ds_read_b128 v[16:19], v10 offset:16
	v_pk_add_f32 v[20:21], v[20:21], 1.0 op_sel_hi:[1,0]
	s_waitcnt lgkmcnt(1)
	v_div_scale_f32 v11, s[20:21], v21, v21, v13
	v_rcp_f32_e32 v28, v11
	s_nop 0
	v_fma_f32 v29, -v11, v28, 1.0
	v_fmac_f32_e32 v28, v29, v28
	v_div_scale_f32 v29, vcc, v13, v21, v13
	v_mul_f32_e32 v30, v29, v28
	v_fma_f32 v31, -v11, v30, v29
	v_fmac_f32_e32 v30, v31, v28
	v_fma_f32 v11, -v11, v30, v29
	v_div_fmas_f32 v11, v11, v28, v30
	v_div_fixup_f32 v13, v11, v21, v13
	v_div_scale_f32 v11, s[20:21], v20, v20, v12
	v_rcp_f32_e32 v21, v11
	s_nop 0
	v_fma_f32 v28, -v11, v21, 1.0
	v_fmac_f32_e32 v21, v28, v21
	v_div_scale_f32 v28, vcc, v12, v20, v12
	v_mul_f32_e32 v29, v28, v21
	v_fma_f32 v30, -v11, v29, v28
	v_fmac_f32_e32 v29, v30, v21
	v_fma_f32 v11, -v11, v29, v28
	v_div_fmas_f32 v11, v11, v21, v29
	v_div_fixup_f32 v12, v11, v20, v12
	v_add_f32_e32 v11, v6, v22
	v_mul_f32_e32 v11, 0xbfb8aa3b, v11
	v_pk_add_f32 v[126:127], v[126:127], v[12:13]
	v_exp_f32_e32 v12, v11
	v_add_f32_e32 v11, v7, v23
	v_mul_f32_e32 v11, 0xbfb8aa3b, v11
	v_exp_f32_e32 v13, v11
	s_nop 0
	v_pk_add_f32 v[12:13], v[12:13], 1.0 op_sel_hi:[1,0]
	s_nop 0
	v_div_scale_f32 v11, s[20:21], v13, v13, v15
	v_rcp_f32_e32 v20, v11
	s_nop 0
	v_fma_f32 v21, -v11, v20, 1.0
	v_fmac_f32_e32 v20, v21, v20
	v_div_scale_f32 v21, vcc, v15, v13, v15
	v_mul_f32_e32 v22, v21, v20
	v_fma_f32 v23, -v11, v22, v21
	v_fmac_f32_e32 v22, v23, v20
	v_fma_f32 v11, -v11, v22, v21
	v_div_fmas_f32 v11, v11, v20, v22
	v_div_fixup_f32 v13, v11, v13, v15
	v_div_scale_f32 v11, s[20:21], v12, v12, v14
	v_rcp_f32_e32 v15, v11
	s_nop 0
	v_fma_f32 v20, -v11, v15, 1.0
	v_fmac_f32_e32 v15, v20, v15
	v_div_scale_f32 v20, vcc, v14, v12, v14
	v_mul_f32_e32 v21, v20, v15
	v_fma_f32 v22, -v11, v21, v20
	v_fmac_f32_e32 v21, v22, v15
	v_fma_f32 v11, -v11, v21, v20
	v_div_fmas_f32 v11, v11, v15, v21
	v_div_fixup_f32 v12, v11, v12, v14
	v_add_f32_e32 v11, v0, v24
	v_mul_f32_e32 v11, 0xbfb8aa3b, v11
	v_pk_add_f32 v[124:125], v[124:125], v[12:13]
	v_exp_f32_e32 v12, v11
	v_add_f32_e32 v11, v1, v25
	v_mul_f32_e32 v11, 0xbfb8aa3b, v11
	v_exp_f32_e32 v13, v11
	s_nop 0
	v_pk_add_f32 v[12:13], v[12:13], 1.0 op_sel_hi:[1,0]
	s_waitcnt lgkmcnt(0)
	v_div_scale_f32 v11, s[20:21], v13, v13, v17
	v_rcp_f32_e32 v14, v11
	s_nop 0
	v_fma_f32 v15, -v11, v14, 1.0
	v_fmac_f32_e32 v14, v15, v14
	v_div_scale_f32 v15, vcc, v17, v13, v17
	v_mul_f32_e32 v20, v15, v14
	v_fma_f32 v21, -v11, v20, v15
	v_fmac_f32_e32 v20, v21, v14
	v_fma_f32 v11, -v11, v20, v15
	v_div_fmas_f32 v11, v11, v14, v20
	v_div_fixup_f32 v13, v11, v13, v17
	v_div_scale_f32 v11, s[20:21], v12, v12, v16
	v_rcp_f32_e32 v14, v11
	s_nop 0
	v_fma_f32 v15, -v11, v14, 1.0
	v_fmac_f32_e32 v14, v15, v14
	v_div_scale_f32 v15, vcc, v16, v12, v16
	v_mul_f32_e32 v17, v15, v14
	v_fma_f32 v20, -v11, v17, v15
	v_fmac_f32_e32 v17, v20, v14
	v_fma_f32 v11, -v11, v17, v15
	v_div_fmas_f32 v11, v11, v14, v17
	v_div_fixup_f32 v12, v11, v12, v16
	v_add_f32_e32 v11, v2, v26
	v_mul_f32_e32 v11, 0xbfb8aa3b, v11
	v_pk_add_f32 v[120:121], v[120:121], v[12:13]
	v_exp_f32_e32 v12, v11
	v_add_f32_e32 v11, v3, v27
	v_mul_f32_e32 v11, 0xbfb8aa3b, v11
	v_exp_f32_e32 v13, v11
	s_nop 0
	v_pk_add_f32 v[12:13], v[12:13], 1.0 op_sel_hi:[1,0]
	s_nop 0
	v_div_scale_f32 v11, s[20:21], v13, v13, v19
	v_rcp_f32_e32 v14, v11
	s_nop 0
	v_fma_f32 v15, -v11, v14, 1.0
	v_fmac_f32_e32 v14, v15, v14
	v_div_scale_f32 v15, vcc, v19, v13, v19
	v_mul_f32_e32 v16, v15, v14
	v_fma_f32 v17, -v11, v16, v15
	v_fmac_f32_e32 v16, v17, v14
	v_fma_f32 v11, -v11, v16, v15
	v_div_fmas_f32 v11, v11, v14, v16
	v_div_fixup_f32 v13, v11, v13, v19
	v_div_scale_f32 v11, s[20:21], v12, v12, v18
	v_rcp_f32_e32 v14, v11
	s_mov_b32 s20, 0xcc31000
	v_fma_f32 v15, -v11, v14, 1.0
	v_fmac_f32_e32 v14, v15, v14
	v_div_scale_f32 v15, vcc, v18, v12, v18
	v_mul_f32_e32 v16, v15, v14
	v_fma_f32 v17, -v11, v16, v15
	v_fmac_f32_e32 v16, v17, v14
	v_fma_f32 v11, -v11, v16, v15
	v_div_fmas_f32 v11, v11, v14, v16
	v_div_fixup_f32 v12, v11, v12, v18
	v_pk_add_f32 v[104:105], v[104:105], v[12:13]
	s_waitcnt vmcnt(6)
	v_mov_b32_e32 v12, v32
	v_mov_b32_e32 v13, v33
	v_mov_b32_e32 v14, v34
	v_mov_b32_e32 v15, v35
	v_lshlrev_b32_e32 v11, 16, v12
	v_add_f32_e32 v11, v4, v11
	v_and_b32_e32 v12, 0xffff0000, v12
	v_mul_f32_e32 v11, 0xbfb8aa3b, v11
	v_exp_f32_e32 v16, v11
	v_add_f32_e32 v11, v5, v12
	v_mul_f32_e32 v11, 0xbfb8aa3b, v11
	v_lshlrev_b32_e32 v18, 16, v13
	v_and_b32_e32 v19, 0xffff0000, v13
	v_lshlrev_b32_e32 v20, 16, v14
	v_and_b32_e32 v21, 0xffff0000, v14
	v_lshlrev_b32_e32 v22, 16, v15
	v_and_b32_e32 v23, 0xffff0000, v15
	v_exp_f32_e32 v17, v11
	ds_read_b128 v[12:15], v10 offset:8448
	v_pk_add_f32 v[16:17], v[16:17], 1.0 op_sel_hi:[1,0]
	s_waitcnt lgkmcnt(0)
	v_div_scale_f32 v11, s[20:21], v17, v17, v13
	v_rcp_f32_e32 v24, v11
	s_nop 0
	v_fma_f32 v25, -v11, v24, 1.0
	v_fmac_f32_e32 v24, v25, v24
	v_div_scale_f32 v25, vcc, v13, v17, v13
	v_mul_f32_e32 v26, v25, v24
	v_fma_f32 v27, -v11, v26, v25
	v_fmac_f32_e32 v26, v27, v24
	v_fma_f32 v11, -v11, v26, v25
	v_div_fmas_f32 v11, v11, v24, v26
	v_div_fixup_f32 v13, v11, v17, v13
	v_div_scale_f32 v11, s[20:21], v16, v16, v12
	v_rcp_f32_e32 v17, v11
	s_nop 0
	v_fma_f32 v24, -v11, v17, 1.0
	v_fmac_f32_e32 v17, v24, v17
	v_div_scale_f32 v24, vcc, v12, v16, v12
	v_mul_f32_e32 v25, v24, v17
	v_fma_f32 v26, -v11, v25, v24
	v_fmac_f32_e32 v25, v26, v17
	v_fma_f32 v11, -v11, v25, v24
	v_div_fmas_f32 v11, v11, v17, v25
	v_div_fixup_f32 v12, v11, v16, v12
	v_add_f32_e32 v11, v6, v18
	v_mul_f32_e32 v11, 0xbfb8aa3b, v11
	v_pk_add_f32 v[122:123], v[122:123], v[12:13]
	v_exp_f32_e32 v12, v11
	v_add_f32_e32 v11, v7, v19
	v_mul_f32_e32 v11, 0xbfb8aa3b, v11
	v_exp_f32_e32 v13, v11
	s_nop 0
	v_pk_add_f32 v[12:13], v[12:13], 1.0 op_sel_hi:[1,0]
	s_nop 0
	v_div_scale_f32 v11, s[20:21], v13, v13, v15
	v_rcp_f32_e32 v16, v11
	s_nop 0
	v_fma_f32 v17, -v11, v16, 1.0
	v_fmac_f32_e32 v16, v17, v16
	v_div_scale_f32 v17, vcc, v15, v13, v15
	v_mul_f32_e32 v18, v17, v16
	v_fma_f32 v19, -v11, v18, v17
	v_fmac_f32_e32 v18, v19, v16
	v_fma_f32 v11, -v11, v18, v17
	v_div_fmas_f32 v11, v11, v16, v18
	v_div_fixup_f32 v13, v11, v13, v15
	v_div_scale_f32 v11, s[20:21], v12, v12, v14
	v_rcp_f32_e32 v15, v11
	s_nop 0
	v_fma_f32 v16, -v11, v15, 1.0
	v_fmac_f32_e32 v15, v16, v15
	v_div_scale_f32 v16, vcc, v14, v12, v14
	v_mul_f32_e32 v17, v16, v15
	v_fma_f32 v18, -v11, v17, v16
	v_fmac_f32_e32 v17, v18, v15
	v_fma_f32 v11, -v11, v17, v16
	v_div_fmas_f32 v11, v11, v15, v17
	v_div_fixup_f32 v12, v11, v12, v14
	v_add_f32_e32 v11, v0, v20
	v_mul_f32_e32 v11, 0xbfb8aa3b, v11
	v_exp_f32_e32 v16, v11
	v_add_f32_e32 v11, v1, v21
	v_mul_f32_e32 v11, 0xbfb8aa3b, v11
	v_pk_add_f32 v[118:119], v[118:119], v[12:13]
	v_exp_f32_e32 v17, v11
	ds_read_b128 v[12:15], v10 offset:8464
	v_pk_add_f32 v[16:17], v[16:17], 1.0 op_sel_hi:[1,0]
	s_waitcnt lgkmcnt(0)
	v_div_scale_f32 v11, s[20:21], v17, v17, v13
	v_rcp_f32_e32 v18, v11
	s_nop 0
	v_fma_f32 v19, -v11, v18, 1.0
	v_fmac_f32_e32 v18, v19, v18
	v_div_scale_f32 v19, vcc, v13, v17, v13
	v_mul_f32_e32 v20, v19, v18
	v_fma_f32 v21, -v11, v20, v19
	v_fmac_f32_e32 v20, v21, v18
	v_fma_f32 v11, -v11, v20, v19
	v_div_fmas_f32 v11, v11, v18, v20
	v_div_fixup_f32 v13, v11, v17, v13
	v_div_scale_f32 v11, s[20:21], v16, v16, v12
	v_rcp_f32_e32 v17, v11
	s_nop 0
	v_fma_f32 v18, -v11, v17, 1.0
	v_fmac_f32_e32 v17, v18, v17
	v_div_scale_f32 v18, vcc, v12, v16, v12
	v_mul_f32_e32 v19, v18, v17
	v_fma_f32 v20, -v11, v19, v18
	v_fmac_f32_e32 v19, v20, v17
	v_fma_f32 v11, -v11, v19, v18
	v_div_fmas_f32 v11, v11, v17, v19
	v_div_fixup_f32 v12, v11, v16, v12
	v_add_f32_e32 v11, v2, v22
	v_mul_f32_e32 v11, 0xbfb8aa3b, v11
	v_pk_add_f32 v[114:115], v[114:115], v[12:13]
	v_exp_f32_e32 v12, v11
	v_add_f32_e32 v11, v3, v23
	v_mul_f32_e32 v11, 0xbfb8aa3b, v11
	v_exp_f32_e32 v13, v11
	s_nop 0
	v_pk_add_f32 v[12:13], v[12:13], 1.0 op_sel_hi:[1,0]
	s_nop 0
	v_div_scale_f32 v11, s[20:21], v13, v13, v15
	v_rcp_f32_e32 v16, v11
	s_nop 0
	v_fma_f32 v17, -v11, v16, 1.0
	v_fmac_f32_e32 v16, v17, v16
	v_div_scale_f32 v17, vcc, v15, v13, v15
	v_mul_f32_e32 v18, v17, v16
	v_fma_f32 v19, -v11, v18, v17
	v_fmac_f32_e32 v18, v19, v16
	v_fma_f32 v11, -v11, v18, v17
	v_div_fmas_f32 v11, v11, v16, v18
	v_div_fixup_f32 v13, v11, v13, v15
	v_div_scale_f32 v11, s[20:21], v12, v12, v14
	v_rcp_f32_e32 v15, v11
	s_mov_b32 s20, 0xcc61000
	v_fma_f32 v16, -v11, v15, 1.0
	v_fmac_f32_e32 v15, v16, v15
	v_div_scale_f32 v16, vcc, v14, v12, v14
	v_mul_f32_e32 v17, v16, v15
	v_fma_f32 v18, -v11, v17, v16
	v_fmac_f32_e32 v17, v18, v15
	v_fma_f32 v11, -v11, v17, v16
	v_div_fmas_f32 v11, v11, v15, v17
	v_div_fixup_f32 v12, v11, v12, v14
	v_pk_add_f32 v[110:111], v[110:111], v[12:13]
	s_waitcnt vmcnt(5)
	v_mov_b32_e32 v12, v36
	v_mov_b32_e32 v13, v37
	v_mov_b32_e32 v14, v38
	v_mov_b32_e32 v15, v39
	v_lshlrev_b32_e32 v11, 16, v12
	v_add_f32_e32 v11, v4, v11
	v_and_b32_e32 v12, 0xffff0000, v12
	v_mul_f32_e32 v11, 0xbfb8aa3b, v11
	v_exp_f32_e32 v16, v11
	v_add_f32_e32 v11, v5, v12
	v_mul_f32_e32 v11, 0xbfb8aa3b, v11
	v_lshlrev_b32_e32 v18, 16, v13
	v_and_b32_e32 v19, 0xffff0000, v13
	v_lshlrev_b32_e32 v20, 16, v14
	v_and_b32_e32 v21, 0xffff0000, v14
	v_lshlrev_b32_e32 v22, 16, v15
	v_and_b32_e32 v23, 0xffff0000, v15
	v_exp_f32_e32 v17, v11
	ds_read_b128 v[12:15], v10 offset:16896
	v_pk_add_f32 v[16:17], v[16:17], 1.0 op_sel_hi:[1,0]
	s_waitcnt lgkmcnt(0)
	v_div_scale_f32 v11, s[20:21], v17, v17, v13
	v_rcp_f32_e32 v24, v11
	s_nop 0
	v_fma_f32 v25, -v11, v24, 1.0
	v_fmac_f32_e32 v24, v25, v24
	v_div_scale_f32 v25, vcc, v13, v17, v13
	v_mul_f32_e32 v26, v25, v24
	v_fma_f32 v27, -v11, v26, v25
	v_fmac_f32_e32 v26, v27, v24
	v_fma_f32 v11, -v11, v26, v25
	v_div_fmas_f32 v11, v11, v24, v26
	v_div_fixup_f32 v13, v11, v17, v13
	v_div_scale_f32 v11, s[20:21], v16, v16, v12
	v_rcp_f32_e32 v17, v11
	s_nop 0
	v_fma_f32 v24, -v11, v17, 1.0
	v_fmac_f32_e32 v17, v24, v17
	v_div_scale_f32 v24, vcc, v12, v16, v12
	v_mul_f32_e32 v25, v24, v17
	v_fma_f32 v26, -v11, v25, v24
	v_fmac_f32_e32 v25, v26, v17
	v_fma_f32 v11, -v11, v25, v24
	v_div_fmas_f32 v11, v11, v17, v25
	v_div_fixup_f32 v12, v11, v16, v12
	v_add_f32_e32 v11, v6, v18
	v_mul_f32_e32 v11, 0xbfb8aa3b, v11
	v_pk_add_f32 v[116:117], v[116:117], v[12:13]
	v_exp_f32_e32 v12, v11
	v_add_f32_e32 v11, v7, v19
	v_mul_f32_e32 v11, 0xbfb8aa3b, v11
	v_exp_f32_e32 v13, v11
	s_nop 0
	v_pk_add_f32 v[12:13], v[12:13], 1.0 op_sel_hi:[1,0]
	s_nop 0
	v_div_scale_f32 v11, s[20:21], v13, v13, v15
	v_rcp_f32_e32 v16, v11
	s_nop 0
	v_fma_f32 v17, -v11, v16, 1.0
	v_fmac_f32_e32 v16, v17, v16
	v_div_scale_f32 v17, vcc, v15, v13, v15
	v_mul_f32_e32 v18, v17, v16
	v_fma_f32 v19, -v11, v18, v17
	v_fmac_f32_e32 v18, v19, v16
	v_fma_f32 v11, -v11, v18, v17
	v_div_fmas_f32 v11, v11, v16, v18
	v_div_fixup_f32 v13, v11, v13, v15
	v_div_scale_f32 v11, s[20:21], v12, v12, v14
	v_rcp_f32_e32 v15, v11
	s_nop 0
	v_fma_f32 v16, -v11, v15, 1.0
	v_fmac_f32_e32 v15, v16, v15
	v_div_scale_f32 v16, vcc, v14, v12, v14
	v_mul_f32_e32 v17, v16, v15
	v_fma_f32 v18, -v11, v17, v16
	v_fmac_f32_e32 v17, v18, v15
	v_fma_f32 v11, -v11, v17, v16
	v_div_fmas_f32 v11, v11, v15, v17
	v_div_fixup_f32 v12, v11, v12, v14
	v_add_f32_e32 v11, v0, v20
	v_mul_f32_e32 v11, 0xbfb8aa3b, v11
	v_exp_f32_e32 v16, v11
	v_add_f32_e32 v11, v1, v21
	v_mul_f32_e32 v11, 0xbfb8aa3b, v11
	v_pk_add_f32 v[112:113], v[112:113], v[12:13]
	v_exp_f32_e32 v17, v11
	ds_read_b128 v[12:15], v10 offset:16912
	v_pk_add_f32 v[16:17], v[16:17], 1.0 op_sel_hi:[1,0]
	s_waitcnt lgkmcnt(0)
	v_div_scale_f32 v11, s[20:21], v17, v17, v13
	v_rcp_f32_e32 v18, v11
	s_nop 0
	v_fma_f32 v19, -v11, v18, 1.0
	v_fmac_f32_e32 v18, v19, v18
	v_div_scale_f32 v19, vcc, v13, v17, v13
	v_mul_f32_e32 v20, v19, v18
	v_fma_f32 v21, -v11, v20, v19
	v_fmac_f32_e32 v20, v21, v18
	v_fma_f32 v11, -v11, v20, v19
	v_div_fmas_f32 v11, v11, v18, v20
	v_div_fixup_f32 v13, v11, v17, v13
	v_div_scale_f32 v11, s[20:21], v16, v16, v12
	v_rcp_f32_e32 v17, v11
	s_nop 0
	v_fma_f32 v18, -v11, v17, 1.0
	v_fmac_f32_e32 v17, v18, v17
	v_div_scale_f32 v18, vcc, v12, v16, v12
	v_mul_f32_e32 v19, v18, v17
	v_fma_f32 v20, -v11, v19, v18
	v_fmac_f32_e32 v19, v20, v17
	v_fma_f32 v11, -v11, v19, v18
	v_div_fmas_f32 v11, v11, v17, v19
	v_div_fixup_f32 v12, v11, v16, v12
	v_add_f32_e32 v11, v2, v22
	v_mul_f32_e32 v11, 0xbfb8aa3b, v11
	v_pk_add_f32 v[106:107], v[106:107], v[12:13]
	v_exp_f32_e32 v12, v11
	v_add_f32_e32 v11, v3, v23
	v_mul_f32_e32 v11, 0xbfb8aa3b, v11
	v_exp_f32_e32 v13, v11
	s_nop 0
	v_pk_add_f32 v[12:13], v[12:13], 1.0 op_sel_hi:[1,0]
	s_nop 0
	v_div_scale_f32 v11, s[20:21], v13, v13, v15
	v_rcp_f32_e32 v16, v11
	s_nop 0
	v_fma_f32 v17, -v11, v16, 1.0
	v_fmac_f32_e32 v16, v17, v16
	v_div_scale_f32 v17, vcc, v15, v13, v15
	v_mul_f32_e32 v18, v17, v16
	v_fma_f32 v19, -v11, v18, v17
	v_fmac_f32_e32 v18, v19, v16
	v_fma_f32 v11, -v11, v18, v17
	v_div_fmas_f32 v11, v11, v16, v18
	v_div_fixup_f32 v13, v11, v13, v15
	v_div_scale_f32 v11, s[20:21], v12, v12, v14
	v_rcp_f32_e32 v15, v11
	s_mov_b32 s20, 0xcc91000
	v_fma_f32 v16, -v11, v15, 1.0
	v_fmac_f32_e32 v15, v16, v15
	v_div_scale_f32 v16, vcc, v14, v12, v14
	v_mul_f32_e32 v17, v16, v15
	v_fma_f32 v18, -v11, v17, v16
	v_fmac_f32_e32 v17, v18, v15
	v_fma_f32 v11, -v11, v17, v16
	v_div_fmas_f32 v11, v11, v15, v17
	v_div_fixup_f32 v12, v11, v12, v14
	v_pk_add_f32 v[100:101], v[100:101], v[12:13]
	s_waitcnt vmcnt(4)
	v_mov_b32_e32 v12, v40
	v_mov_b32_e32 v13, v41
	v_mov_b32_e32 v14, v42
	v_mov_b32_e32 v15, v43
	v_lshlrev_b32_e32 v11, 16, v12
	v_add_f32_e32 v11, v4, v11
	v_and_b32_e32 v12, 0xffff0000, v12
	v_mul_f32_e32 v11, 0xbfb8aa3b, v11
	v_exp_f32_e32 v16, v11
	v_add_f32_e32 v11, v5, v12
	v_mul_f32_e32 v11, 0xbfb8aa3b, v11
	v_lshlrev_b32_e32 v18, 16, v13
	v_and_b32_e32 v19, 0xffff0000, v13
	v_lshlrev_b32_e32 v20, 16, v14
	v_and_b32_e32 v21, 0xffff0000, v14
	v_lshlrev_b32_e32 v22, 16, v15
	v_and_b32_e32 v23, 0xffff0000, v15
	v_exp_f32_e32 v17, v11
	ds_read_b128 v[12:15], v10 offset:25344
	v_pk_add_f32 v[16:17], v[16:17], 1.0 op_sel_hi:[1,0]
	s_waitcnt lgkmcnt(0)
	v_div_scale_f32 v11, s[20:21], v17, v17, v13
	v_rcp_f32_e32 v24, v11
	s_nop 0
	v_fma_f32 v25, -v11, v24, 1.0
	v_fmac_f32_e32 v24, v25, v24
	v_div_scale_f32 v25, vcc, v13, v17, v13
	v_mul_f32_e32 v26, v25, v24
	v_fma_f32 v27, -v11, v26, v25
	v_fmac_f32_e32 v26, v27, v24
	v_fma_f32 v11, -v11, v26, v25
	v_div_fmas_f32 v11, v11, v24, v26
	v_div_fixup_f32 v13, v11, v17, v13
	v_div_scale_f32 v11, s[20:21], v16, v16, v12
	v_rcp_f32_e32 v17, v11
	s_nop 0
	v_fma_f32 v24, -v11, v17, 1.0
	v_fmac_f32_e32 v17, v24, v17
	v_div_scale_f32 v24, vcc, v12, v16, v12
	v_mul_f32_e32 v25, v24, v17
	v_fma_f32 v26, -v11, v25, v24
	v_fmac_f32_e32 v25, v26, v17
	v_fma_f32 v11, -v11, v25, v24
	v_div_fmas_f32 v11, v11, v17, v25
	v_div_fixup_f32 v12, v11, v16, v12
	v_add_f32_e32 v11, v6, v18
	v_mul_f32_e32 v11, 0xbfb8aa3b, v11
	v_pk_add_f32 v[108:109], v[108:109], v[12:13]
	v_exp_f32_e32 v12, v11
	v_add_f32_e32 v11, v7, v19
	v_mul_f32_e32 v11, 0xbfb8aa3b, v11
	v_exp_f32_e32 v13, v11
	s_nop 0
	v_pk_add_f32 v[12:13], v[12:13], 1.0 op_sel_hi:[1,0]
	s_nop 0
	v_div_scale_f32 v11, s[20:21], v13, v13, v15
	v_rcp_f32_e32 v16, v11
	s_nop 0
	v_fma_f32 v17, -v11, v16, 1.0
	v_fmac_f32_e32 v16, v17, v16
	v_div_scale_f32 v17, vcc, v15, v13, v15
	v_mul_f32_e32 v18, v17, v16
	v_fma_f32 v19, -v11, v18, v17
	v_fmac_f32_e32 v18, v19, v16
	v_fma_f32 v11, -v11, v18, v17
	v_div_fmas_f32 v11, v11, v16, v18
	v_div_fixup_f32 v13, v11, v13, v15
	v_div_scale_f32 v11, s[20:21], v12, v12, v14
	v_rcp_f32_e32 v15, v11
	s_nop 0
	v_fma_f32 v16, -v11, v15, 1.0
	v_fmac_f32_e32 v15, v16, v15
	v_div_scale_f32 v16, vcc, v14, v12, v14
	v_mul_f32_e32 v17, v16, v15
	v_fma_f32 v18, -v11, v17, v16
	v_fmac_f32_e32 v17, v18, v15
	v_fma_f32 v11, -v11, v17, v16
	v_div_fmas_f32 v11, v11, v15, v17
	v_div_fixup_f32 v12, v11, v12, v14
	v_add_f32_e32 v11, v0, v20
	v_mul_f32_e32 v11, 0xbfb8aa3b, v11
	v_exp_f32_e32 v16, v11
	v_add_f32_e32 v11, v1, v21
	v_mul_f32_e32 v11, 0xbfb8aa3b, v11
	v_pk_add_f32 v[102:103], v[102:103], v[12:13]
	v_exp_f32_e32 v17, v11
	ds_read_b128 v[12:15], v10 offset:25360
	v_pk_add_f32 v[16:17], v[16:17], 1.0 op_sel_hi:[1,0]
	s_waitcnt lgkmcnt(0)
	v_div_scale_f32 v11, s[20:21], v17, v17, v13
	v_rcp_f32_e32 v18, v11
	s_nop 0
	v_fma_f32 v19, -v11, v18, 1.0
	v_fmac_f32_e32 v18, v19, v18
	v_div_scale_f32 v19, vcc, v13, v17, v13
	v_mul_f32_e32 v20, v19, v18
	v_fma_f32 v21, -v11, v20, v19
	v_fmac_f32_e32 v20, v21, v18
	v_fma_f32 v11, -v11, v20, v19
	v_div_fmas_f32 v11, v11, v18, v20
	v_div_fixup_f32 v13, v11, v17, v13
	v_div_scale_f32 v11, s[20:21], v16, v16, v12
	v_rcp_f32_e32 v17, v11
	s_nop 0
	v_fma_f32 v18, -v11, v17, 1.0
	v_fmac_f32_e32 v17, v18, v17
	v_div_scale_f32 v18, vcc, v12, v16, v12
	v_mul_f32_e32 v19, v18, v17
	v_fma_f32 v20, -v11, v19, v18
	v_fmac_f32_e32 v19, v20, v17
	v_fma_f32 v11, -v11, v19, v18
	v_div_fmas_f32 v11, v11, v17, v19
	v_div_fixup_f32 v12, v11, v16, v12
	v_add_f32_e32 v11, v2, v22
	v_mul_f32_e32 v11, 0xbfb8aa3b, v11
	v_pk_add_f32 v[96:97], v[96:97], v[12:13]
	v_exp_f32_e32 v12, v11
	v_add_f32_e32 v11, v3, v23
	v_mul_f32_e32 v11, 0xbfb8aa3b, v11
	v_exp_f32_e32 v13, v11
	s_nop 0
	v_pk_add_f32 v[12:13], v[12:13], 1.0 op_sel_hi:[1,0]
	s_nop 0
	v_div_scale_f32 v11, s[20:21], v13, v13, v15
	v_rcp_f32_e32 v16, v11
	s_nop 0
	v_fma_f32 v17, -v11, v16, 1.0
	v_fmac_f32_e32 v16, v17, v16
	v_div_scale_f32 v17, vcc, v15, v13, v15
	v_mul_f32_e32 v18, v17, v16
	v_fma_f32 v19, -v11, v18, v17
	v_fmac_f32_e32 v18, v19, v16
	v_fma_f32 v11, -v11, v18, v17
	v_div_fmas_f32 v11, v11, v16, v18
	v_div_fixup_f32 v13, v11, v13, v15
	v_div_scale_f32 v11, s[20:21], v12, v12, v14
	v_rcp_f32_e32 v15, v11
	s_mov_b32 s20, 0xccc1000
	v_fma_f32 v16, -v11, v15, 1.0
	v_fmac_f32_e32 v15, v16, v15
	v_div_scale_f32 v16, vcc, v14, v12, v14
	v_mul_f32_e32 v17, v16, v15
	v_fma_f32 v18, -v11, v17, v16
	v_fmac_f32_e32 v17, v18, v15
	v_fma_f32 v11, -v11, v17, v16
	v_div_fmas_f32 v11, v11, v15, v17
	v_div_fixup_f32 v12, v11, v12, v14
	v_pk_add_f32 v[92:93], v[92:93], v[12:13]
	s_waitcnt vmcnt(3)
	v_mov_b32_e32 v12, v44
	v_mov_b32_e32 v13, v45
	v_mov_b32_e32 v14, v46
	v_mov_b32_e32 v15, v47
	v_lshlrev_b32_e32 v11, 16, v12
	v_add_f32_e32 v11, v4, v11
	v_and_b32_e32 v12, 0xffff0000, v12
	v_mul_f32_e32 v11, 0xbfb8aa3b, v11
	v_exp_f32_e32 v16, v11
	v_add_f32_e32 v11, v5, v12
	v_mul_f32_e32 v11, 0xbfb8aa3b, v11
	v_lshlrev_b32_e32 v18, 16, v13
	v_and_b32_e32 v19, 0xffff0000, v13
	v_lshlrev_b32_e32 v20, 16, v14
	v_and_b32_e32 v21, 0xffff0000, v14
	v_lshlrev_b32_e32 v22, 16, v15
	v_and_b32_e32 v23, 0xffff0000, v15
	v_exp_f32_e32 v17, v11
	ds_read_b128 v[12:15], v10 offset:33792
	v_pk_add_f32 v[16:17], v[16:17], 1.0 op_sel_hi:[1,0]
	s_waitcnt lgkmcnt(0)
	v_div_scale_f32 v11, s[20:21], v17, v17, v13
	v_rcp_f32_e32 v24, v11
	s_nop 0
	v_fma_f32 v25, -v11, v24, 1.0
	v_fmac_f32_e32 v24, v25, v24
	v_div_scale_f32 v25, vcc, v13, v17, v13
	v_mul_f32_e32 v26, v25, v24
	v_fma_f32 v27, -v11, v26, v25
	v_fmac_f32_e32 v26, v27, v24
	v_fma_f32 v11, -v11, v26, v25
	v_div_fmas_f32 v11, v11, v24, v26
	v_div_fixup_f32 v13, v11, v17, v13
	v_div_scale_f32 v11, s[20:21], v16, v16, v12
	v_rcp_f32_e32 v17, v11
	s_nop 0
	v_fma_f32 v24, -v11, v17, 1.0
	v_fmac_f32_e32 v17, v24, v17
	v_div_scale_f32 v24, vcc, v12, v16, v12
	v_mul_f32_e32 v25, v24, v17
	v_fma_f32 v26, -v11, v25, v24
	v_fmac_f32_e32 v25, v26, v17
	v_fma_f32 v11, -v11, v25, v24
	v_div_fmas_f32 v11, v11, v17, v25
	v_div_fixup_f32 v12, v11, v16, v12
	v_add_f32_e32 v11, v6, v18
	v_mul_f32_e32 v11, 0xbfb8aa3b, v11
	v_pk_add_f32 v[98:99], v[98:99], v[12:13]
	v_exp_f32_e32 v12, v11
	v_add_f32_e32 v11, v7, v19
	v_mul_f32_e32 v11, 0xbfb8aa3b, v11
	v_exp_f32_e32 v13, v11
	s_nop 0
	v_pk_add_f32 v[12:13], v[12:13], 1.0 op_sel_hi:[1,0]
	s_nop 0
	v_div_scale_f32 v11, s[20:21], v13, v13, v15
	v_rcp_f32_e32 v16, v11
	s_nop 0
	v_fma_f32 v17, -v11, v16, 1.0
	v_fmac_f32_e32 v16, v17, v16
	v_div_scale_f32 v17, vcc, v15, v13, v15
	v_mul_f32_e32 v18, v17, v16
	v_fma_f32 v19, -v11, v18, v17
	v_fmac_f32_e32 v18, v19, v16
	v_fma_f32 v11, -v11, v18, v17
	v_div_fmas_f32 v11, v11, v16, v18
	v_div_fixup_f32 v13, v11, v13, v15
	v_div_scale_f32 v11, s[20:21], v12, v12, v14
	v_rcp_f32_e32 v15, v11
	s_nop 0
	v_fma_f32 v16, -v11, v15, 1.0
	v_fmac_f32_e32 v15, v16, v15
	v_div_scale_f32 v16, vcc, v14, v12, v14
	v_mul_f32_e32 v17, v16, v15
	v_fma_f32 v18, -v11, v17, v16
	v_fmac_f32_e32 v17, v18, v15
	v_fma_f32 v11, -v11, v17, v16
	v_div_fmas_f32 v11, v11, v15, v17
	v_div_fixup_f32 v12, v11, v12, v14
	v_add_f32_e32 v11, v0, v20
	v_mul_f32_e32 v11, 0xbfb8aa3b, v11
	v_exp_f32_e32 v16, v11
	v_add_f32_e32 v11, v1, v21
	v_mul_f32_e32 v11, 0xbfb8aa3b, v11
	v_pk_add_f32 v[94:95], v[94:95], v[12:13]
	v_exp_f32_e32 v17, v11
	ds_read_b128 v[12:15], v10 offset:33808
	v_pk_add_f32 v[16:17], v[16:17], 1.0 op_sel_hi:[1,0]
	s_waitcnt lgkmcnt(0)
	v_div_scale_f32 v11, s[20:21], v17, v17, v13
	v_rcp_f32_e32 v18, v11
	s_nop 0
	v_fma_f32 v19, -v11, v18, 1.0
	v_fmac_f32_e32 v18, v19, v18
	v_div_scale_f32 v19, vcc, v13, v17, v13
	v_mul_f32_e32 v20, v19, v18
	v_fma_f32 v21, -v11, v20, v19
	v_fmac_f32_e32 v20, v21, v18
	v_fma_f32 v11, -v11, v20, v19
	v_div_fmas_f32 v11, v11, v18, v20
	v_div_fixup_f32 v13, v11, v17, v13
	v_div_scale_f32 v11, s[20:21], v16, v16, v12
	v_rcp_f32_e32 v17, v11
	s_nop 0
	v_fma_f32 v18, -v11, v17, 1.0
	v_fmac_f32_e32 v17, v18, v17
	v_div_scale_f32 v18, vcc, v12, v16, v12
	v_mul_f32_e32 v19, v18, v17
	v_fma_f32 v20, -v11, v19, v18
	v_fmac_f32_e32 v19, v20, v17
	v_fma_f32 v11, -v11, v19, v18
	v_div_fmas_f32 v11, v11, v17, v19
	v_div_fixup_f32 v12, v11, v16, v12
	v_add_f32_e32 v11, v2, v22
	v_mul_f32_e32 v11, 0xbfb8aa3b, v11
	v_pk_add_f32 v[88:89], v[88:89], v[12:13]
	v_exp_f32_e32 v12, v11
	v_add_f32_e32 v11, v3, v23
	v_mul_f32_e32 v11, 0xbfb8aa3b, v11
	v_exp_f32_e32 v13, v11
	s_nop 0
	v_pk_add_f32 v[12:13], v[12:13], 1.0 op_sel_hi:[1,0]
	s_nop 0
	v_div_scale_f32 v11, s[20:21], v13, v13, v15
	v_rcp_f32_e32 v16, v11
	s_nop 0
	v_fma_f32 v17, -v11, v16, 1.0
	v_fmac_f32_e32 v16, v17, v16
	v_div_scale_f32 v17, vcc, v15, v13, v15
	v_mul_f32_e32 v18, v17, v16
	v_fma_f32 v19, -v11, v18, v17
	v_fmac_f32_e32 v18, v19, v16
	v_fma_f32 v11, -v11, v18, v17
	v_div_fmas_f32 v11, v11, v16, v18
	v_div_fixup_f32 v13, v11, v13, v15
	v_div_scale_f32 v11, s[20:21], v12, v12, v14
	v_rcp_f32_e32 v15, v11
	s_mov_b32 s20, 0xccf1000
	v_fma_f32 v16, -v11, v15, 1.0
	v_fmac_f32_e32 v15, v16, v15
	v_div_scale_f32 v16, vcc, v14, v12, v14
	v_mul_f32_e32 v17, v16, v15
	v_fma_f32 v18, -v11, v17, v16
	v_fmac_f32_e32 v17, v18, v15
	v_fma_f32 v11, -v11, v17, v16
	v_div_fmas_f32 v11, v11, v15, v17
	v_div_fixup_f32 v12, v11, v12, v14
	v_pk_add_f32 v[84:85], v[84:85], v[12:13]
	s_waitcnt vmcnt(2)
	v_mov_b32_e32 v12, v48
	v_mov_b32_e32 v13, v49
	v_mov_b32_e32 v14, v50
	v_mov_b32_e32 v15, v51
	v_lshlrev_b32_e32 v11, 16, v12
	v_add_f32_e32 v11, v4, v11
	v_and_b32_e32 v12, 0xffff0000, v12
	v_mul_f32_e32 v11, 0xbfb8aa3b, v11
	v_exp_f32_e32 v16, v11
	v_add_f32_e32 v11, v5, v12
	v_mul_f32_e32 v11, 0xbfb8aa3b, v11
	v_lshlrev_b32_e32 v18, 16, v13
	v_and_b32_e32 v19, 0xffff0000, v13
	v_lshlrev_b32_e32 v20, 16, v14
	v_and_b32_e32 v21, 0xffff0000, v14
	v_lshlrev_b32_e32 v22, 16, v15
	v_and_b32_e32 v23, 0xffff0000, v15
	v_exp_f32_e32 v17, v11
	ds_read_b128 v[12:15], v10 offset:42240
	v_pk_add_f32 v[16:17], v[16:17], 1.0 op_sel_hi:[1,0]
	s_waitcnt lgkmcnt(0)
	v_div_scale_f32 v11, s[20:21], v17, v17, v13
	v_rcp_f32_e32 v24, v11
	s_nop 0
	v_fma_f32 v25, -v11, v24, 1.0
	v_fmac_f32_e32 v24, v25, v24
	v_div_scale_f32 v25, vcc, v13, v17, v13
	v_mul_f32_e32 v26, v25, v24
	v_fma_f32 v27, -v11, v26, v25
	v_fmac_f32_e32 v26, v27, v24
	v_fma_f32 v11, -v11, v26, v25
	v_div_fmas_f32 v11, v11, v24, v26
	v_div_fixup_f32 v13, v11, v17, v13
	v_div_scale_f32 v11, s[20:21], v16, v16, v12
	v_rcp_f32_e32 v17, v11
	s_nop 0
	v_fma_f32 v24, -v11, v17, 1.0
	v_fmac_f32_e32 v17, v24, v17
	v_div_scale_f32 v24, vcc, v12, v16, v12
	v_mul_f32_e32 v25, v24, v17
	v_fma_f32 v26, -v11, v25, v24
	v_fmac_f32_e32 v25, v26, v17
	v_fma_f32 v11, -v11, v25, v24
	v_div_fmas_f32 v11, v11, v17, v25
	v_div_fixup_f32 v12, v11, v16, v12
	v_add_f32_e32 v11, v6, v18
	v_mul_f32_e32 v11, 0xbfb8aa3b, v11
	v_pk_add_f32 v[90:91], v[90:91], v[12:13]
	v_exp_f32_e32 v12, v11
	v_add_f32_e32 v11, v7, v19
	v_mul_f32_e32 v11, 0xbfb8aa3b, v11
	v_exp_f32_e32 v13, v11
	s_nop 0
	v_pk_add_f32 v[12:13], v[12:13], 1.0 op_sel_hi:[1,0]
	s_nop 0
	v_div_scale_f32 v11, s[20:21], v13, v13, v15
	v_rcp_f32_e32 v16, v11
	s_nop 0
	v_fma_f32 v17, -v11, v16, 1.0
	v_fmac_f32_e32 v16, v17, v16
	v_div_scale_f32 v17, vcc, v15, v13, v15
	v_mul_f32_e32 v18, v17, v16
	v_fma_f32 v19, -v11, v18, v17
	v_fmac_f32_e32 v18, v19, v16
	v_fma_f32 v11, -v11, v18, v17
	v_div_fmas_f32 v11, v11, v16, v18
	v_div_fixup_f32 v13, v11, v13, v15
	v_div_scale_f32 v11, s[20:21], v12, v12, v14
	v_rcp_f32_e32 v15, v11
	s_nop 0
	v_fma_f32 v16, -v11, v15, 1.0
	v_fmac_f32_e32 v15, v16, v15
	v_div_scale_f32 v16, vcc, v14, v12, v14
	v_mul_f32_e32 v17, v16, v15
	v_fma_f32 v18, -v11, v17, v16
	v_fmac_f32_e32 v17, v18, v15
	v_fma_f32 v11, -v11, v17, v16
	v_div_fmas_f32 v11, v11, v15, v17
	v_div_fixup_f32 v12, v11, v12, v14
	v_add_f32_e32 v11, v0, v20
	v_mul_f32_e32 v11, 0xbfb8aa3b, v11
	v_exp_f32_e32 v16, v11
	v_add_f32_e32 v11, v1, v21
	v_mul_f32_e32 v11, 0xbfb8aa3b, v11
	v_pk_add_f32 v[86:87], v[86:87], v[12:13]
	v_exp_f32_e32 v17, v11
	ds_read_b128 v[12:15], v10 offset:42256
	v_pk_add_f32 v[16:17], v[16:17], 1.0 op_sel_hi:[1,0]
	s_waitcnt lgkmcnt(0)
	v_div_scale_f32 v11, s[20:21], v17, v17, v13
	v_rcp_f32_e32 v18, v11
	s_nop 0
	v_fma_f32 v19, -v11, v18, 1.0
	v_fmac_f32_e32 v18, v19, v18
	v_div_scale_f32 v19, vcc, v13, v17, v13
	v_mul_f32_e32 v20, v19, v18
	v_fma_f32 v21, -v11, v20, v19
	v_fmac_f32_e32 v20, v21, v18
	v_fma_f32 v11, -v11, v20, v19
	v_div_fmas_f32 v11, v11, v18, v20
	v_div_fixup_f32 v13, v11, v17, v13
	v_div_scale_f32 v11, s[20:21], v16, v16, v12
	v_rcp_f32_e32 v17, v11
	s_nop 0
	v_fma_f32 v18, -v11, v17, 1.0
	v_fmac_f32_e32 v17, v18, v17
	v_div_scale_f32 v18, vcc, v12, v16, v12
	v_mul_f32_e32 v19, v18, v17
	v_fma_f32 v20, -v11, v19, v18
	v_fmac_f32_e32 v19, v20, v17
	v_fma_f32 v11, -v11, v19, v18
	v_div_fmas_f32 v11, v11, v17, v19
	v_div_fixup_f32 v12, v11, v16, v12
	v_add_f32_e32 v11, v2, v22
	v_mul_f32_e32 v11, 0xbfb8aa3b, v11
	v_pk_add_f32 v[82:83], v[82:83], v[12:13]
	v_exp_f32_e32 v12, v11
	v_add_f32_e32 v11, v3, v23
	v_mul_f32_e32 v11, 0xbfb8aa3b, v11
	v_exp_f32_e32 v13, v11
	s_nop 0
	v_pk_add_f32 v[12:13], v[12:13], 1.0 op_sel_hi:[1,0]
	s_nop 0
	v_div_scale_f32 v11, s[20:21], v13, v13, v15
	v_rcp_f32_e32 v16, v11
	s_nop 0
	v_fma_f32 v17, -v11, v16, 1.0
	v_fmac_f32_e32 v16, v17, v16
	v_div_scale_f32 v17, vcc, v15, v13, v15
	v_mul_f32_e32 v18, v17, v16
	v_fma_f32 v19, -v11, v18, v17
	v_fmac_f32_e32 v18, v19, v16
	v_fma_f32 v11, -v11, v18, v17
	v_div_fmas_f32 v11, v11, v16, v18
	v_div_fixup_f32 v13, v11, v13, v15
	v_div_scale_f32 v11, s[20:21], v12, v12, v14
	v_rcp_f32_e32 v15, v11
	s_mov_b32 s20, 0xcd21000
	v_fma_f32 v16, -v11, v15, 1.0
	v_fmac_f32_e32 v15, v16, v15
	v_div_scale_f32 v16, vcc, v14, v12, v14
	v_mul_f32_e32 v17, v16, v15
	v_fma_f32 v18, -v11, v17, v16
	v_fmac_f32_e32 v17, v18, v15
	v_fma_f32 v11, -v11, v17, v16
	v_div_fmas_f32 v11, v11, v15, v17
	v_div_fixup_f32 v12, v11, v12, v14
	v_pk_add_f32 v[78:79], v[78:79], v[12:13]
	s_waitcnt vmcnt(1)
	v_mov_b32_e32 v12, v52
	v_mov_b32_e32 v13, v53
	v_mov_b32_e32 v14, v54
	v_mov_b32_e32 v15, v55
	v_lshlrev_b32_e32 v11, 16, v12
	v_add_f32_e32 v11, v4, v11
	v_and_b32_e32 v12, 0xffff0000, v12
	v_mul_f32_e32 v11, 0xbfb8aa3b, v11
	v_exp_f32_e32 v16, v11
	v_add_f32_e32 v11, v5, v12
	v_mul_f32_e32 v11, 0xbfb8aa3b, v11
	v_lshlrev_b32_e32 v18, 16, v13
	v_and_b32_e32 v19, 0xffff0000, v13
	v_lshlrev_b32_e32 v20, 16, v14
	v_and_b32_e32 v21, 0xffff0000, v14
	v_lshlrev_b32_e32 v22, 16, v15
	v_and_b32_e32 v23, 0xffff0000, v15
	v_exp_f32_e32 v17, v11
	ds_read_b128 v[12:15], v10 offset:50688
	v_pk_add_f32 v[16:17], v[16:17], 1.0 op_sel_hi:[1,0]
	s_waitcnt lgkmcnt(0)
	v_div_scale_f32 v11, s[20:21], v17, v17, v13
	v_rcp_f32_e32 v24, v11
	s_nop 0
	v_fma_f32 v25, -v11, v24, 1.0
	v_fmac_f32_e32 v24, v25, v24
	v_div_scale_f32 v25, vcc, v13, v17, v13
	v_mul_f32_e32 v26, v25, v24
	v_fma_f32 v27, -v11, v26, v25
	v_fmac_f32_e32 v26, v27, v24
	v_fma_f32 v11, -v11, v26, v25
	v_div_fmas_f32 v11, v11, v24, v26
	v_div_fixup_f32 v13, v11, v17, v13
	v_div_scale_f32 v11, s[20:21], v16, v16, v12
	v_rcp_f32_e32 v17, v11
	s_nop 0
	v_fma_f32 v24, -v11, v17, 1.0
	v_fmac_f32_e32 v17, v24, v17
	v_div_scale_f32 v24, vcc, v12, v16, v12
	v_mul_f32_e32 v25, v24, v17
	v_fma_f32 v26, -v11, v25, v24
	v_fmac_f32_e32 v25, v26, v17
	v_fma_f32 v11, -v11, v25, v24
	v_div_fmas_f32 v11, v11, v17, v25
	v_div_fixup_f32 v12, v11, v16, v12
	v_add_f32_e32 v11, v6, v18
	v_mul_f32_e32 v11, 0xbfb8aa3b, v11
	v_pk_add_f32 v[80:81], v[80:81], v[12:13]
	v_exp_f32_e32 v12, v11
	v_add_f32_e32 v11, v7, v19
	v_mul_f32_e32 v11, 0xbfb8aa3b, v11
	v_exp_f32_e32 v13, v11
	s_nop 0
	v_pk_add_f32 v[12:13], v[12:13], 1.0 op_sel_hi:[1,0]
	s_nop 0
	v_div_scale_f32 v11, s[20:21], v13, v13, v15
	v_rcp_f32_e32 v16, v11
	s_nop 0
	v_fma_f32 v17, -v11, v16, 1.0
	v_fmac_f32_e32 v16, v17, v16
	v_div_scale_f32 v17, vcc, v15, v13, v15
	v_mul_f32_e32 v18, v17, v16
	v_fma_f32 v19, -v11, v18, v17
	v_fmac_f32_e32 v18, v19, v16
	v_fma_f32 v11, -v11, v18, v17
	v_div_fmas_f32 v11, v11, v16, v18
	v_div_fixup_f32 v13, v11, v13, v15
	v_div_scale_f32 v11, s[20:21], v12, v12, v14
	v_rcp_f32_e32 v15, v11
	s_nop 0
	v_fma_f32 v16, -v11, v15, 1.0
	v_fmac_f32_e32 v15, v16, v15
	v_div_scale_f32 v16, vcc, v14, v12, v14
	v_mul_f32_e32 v17, v16, v15
	v_fma_f32 v18, -v11, v17, v16
	v_fmac_f32_e32 v17, v18, v15
	v_fma_f32 v11, -v11, v17, v16
	v_div_fmas_f32 v11, v11, v15, v17
	v_div_fixup_f32 v12, v11, v12, v14
	v_add_f32_e32 v11, v0, v20
	v_mul_f32_e32 v11, 0xbfb8aa3b, v11
	v_exp_f32_e32 v16, v11
	v_add_f32_e32 v11, v1, v21
	v_mul_f32_e32 v11, 0xbfb8aa3b, v11
	v_pk_add_f32 v[76:77], v[76:77], v[12:13]
	v_exp_f32_e32 v17, v11
	ds_read_b128 v[12:15], v10 offset:50704
	v_pk_add_f32 v[16:17], v[16:17], 1.0 op_sel_hi:[1,0]
	s_waitcnt lgkmcnt(0)
	v_div_scale_f32 v11, s[20:21], v17, v17, v13
	v_rcp_f32_e32 v18, v11
	s_nop 0
	v_fma_f32 v19, -v11, v18, 1.0
	v_fmac_f32_e32 v18, v19, v18
	v_div_scale_f32 v19, vcc, v13, v17, v13
	v_mul_f32_e32 v20, v19, v18
	v_fma_f32 v21, -v11, v20, v19
	v_fmac_f32_e32 v20, v21, v18
	v_fma_f32 v11, -v11, v20, v19
	v_div_fmas_f32 v11, v11, v18, v20
	v_div_fixup_f32 v13, v11, v17, v13
	v_div_scale_f32 v11, s[20:21], v16, v16, v12
	v_rcp_f32_e32 v17, v11
	s_nop 0
	v_fma_f32 v18, -v11, v17, 1.0
	v_fmac_f32_e32 v17, v18, v17
	v_div_scale_f32 v18, vcc, v12, v16, v12
	v_mul_f32_e32 v19, v18, v17
	v_fma_f32 v20, -v11, v19, v18
	v_fmac_f32_e32 v19, v20, v17
	v_fma_f32 v11, -v11, v19, v18
	v_div_fmas_f32 v11, v11, v17, v19
	v_div_fixup_f32 v12, v11, v16, v12
	v_add_f32_e32 v11, v2, v22
	v_mul_f32_e32 v11, 0xbfb8aa3b, v11
	v_pk_add_f32 v[74:75], v[74:75], v[12:13]
	v_exp_f32_e32 v12, v11
	v_add_f32_e32 v11, v3, v23
	v_mul_f32_e32 v11, 0xbfb8aa3b, v11
	v_exp_f32_e32 v13, v11
	s_nop 0
	v_pk_add_f32 v[12:13], v[12:13], 1.0 op_sel_hi:[1,0]
	s_nop 0
	v_div_scale_f32 v11, s[20:21], v13, v13, v15
	v_rcp_f32_e32 v16, v11
	s_nop 0
	v_fma_f32 v17, -v11, v16, 1.0
	v_fmac_f32_e32 v16, v17, v16
	v_div_scale_f32 v17, vcc, v15, v13, v15
	v_mul_f32_e32 v18, v17, v16
	v_fma_f32 v19, -v11, v18, v17
	v_fmac_f32_e32 v18, v19, v16
	v_fma_f32 v11, -v11, v18, v17
	v_div_fmas_f32 v11, v11, v16, v18
	v_div_fixup_f32 v13, v11, v13, v15
	v_div_scale_f32 v11, s[20:21], v12, v12, v14
	v_rcp_f32_e32 v15, v11
	s_mov_b32 s20, 0xcd51000
	v_fma_f32 v16, -v11, v15, 1.0
	v_fmac_f32_e32 v15, v16, v15
	v_div_scale_f32 v16, vcc, v14, v12, v14
	v_mul_f32_e32 v17, v16, v15
	v_fma_f32 v18, -v11, v17, v16
	v_fmac_f32_e32 v17, v18, v15
	v_fma_f32 v11, -v11, v17, v16
	v_div_fmas_f32 v11, v11, v15, v17
	v_add_co_u32_e32 v8, vcc, s20, v8
	v_div_fixup_f32 v12, v11, v12, v14
	s_nop 0
	v_addc_co_u32_e32 v9, vcc, 0, v9, vcc
	v_pk_add_f32 v[70:71], v[70:71], v[12:13]
	s_waitcnt vmcnt(0)
	v_mov_b32_e32 v12, v56
	v_mov_b32_e32 v13, v57
	v_mov_b32_e32 v14, v58
	v_mov_b32_e32 v15, v59
	v_lshlrev_b32_e32 v11, 16, v12
	v_and_b32_e32 v12, 0xffff0000, v12
	v_add_f32_e32 v4, v4, v11
	v_add_f32_e32 v5, v5, v12
	v_mul_f32_e32 v4, 0xbfb8aa3b, v4
	v_mul_f32_e32 v5, 0xbfb8aa3b, v5
	v_lshlrev_b32_e32 v16, 16, v13
	v_and_b32_e32 v17, 0xffff0000, v13
	v_lshlrev_b32_e32 v18, 16, v14
	v_and_b32_e32 v19, 0xffff0000, v14
	v_lshlrev_b32_e32 v9, 16, v15
	v_and_b32_e32 v8, 0xffff0000, v15
	v_exp_f32_e32 v4, v4
	v_exp_f32_e32 v5, v5
	ds_read_b128 v[12:15], v10 offset:59136
	v_add_f32_e32 v0, v0, v18
	v_add_f32_e32 v1, v1, v19
	v_pk_add_f32 v[4:5], v[4:5], 1.0 op_sel_hi:[1,0]
	v_mul_f32_e32 v0, 0xbfb8aa3b, v0
	s_waitcnt lgkmcnt(0)
	v_div_scale_f32 v11, s[20:21], v5, v5, v13
	v_rcp_f32_e32 v20, v11
	v_mul_f32_e32 v1, 0xbfb8aa3b, v1
	v_exp_f32_e32 v0, v0
	v_exp_f32_e32 v1, v1
	v_fma_f32 v21, -v11, v20, 1.0
	v_fmac_f32_e32 v20, v21, v20
	v_div_scale_f32 v21, vcc, v13, v5, v13
	v_mul_f32_e32 v22, v21, v20
	v_fma_f32 v23, -v11, v22, v21
	v_fmac_f32_e32 v22, v23, v20
	v_fma_f32 v11, -v11, v22, v21
	v_div_fmas_f32 v11, v11, v20, v22
	v_div_fixup_f32 v5, v11, v5, v13
	v_div_scale_f32 v11, s[20:21], v4, v4, v12
	v_rcp_f32_e32 v13, v11
	v_pk_add_f32 v[0:1], v[0:1], 1.0 op_sel_hi:[1,0]
	v_fma_f32 v20, -v11, v13, 1.0
	v_fmac_f32_e32 v13, v20, v13
	v_div_scale_f32 v20, vcc, v12, v4, v12
	v_mul_f32_e32 v21, v20, v13
	v_fma_f32 v22, -v11, v21, v20
	v_fmac_f32_e32 v21, v22, v13
	v_fma_f32 v11, -v11, v21, v20
	v_div_fmas_f32 v11, v11, v13, v21
	v_div_fixup_f32 v4, v11, v4, v12
	v_pk_add_f32 v[72:73], v[72:73], v[4:5]
	v_add_f32_e32 v4, v6, v16
	v_add_f32_e32 v5, v7, v17
	v_mul_f32_e32 v4, 0xbfb8aa3b, v4
	v_mul_f32_e32 v5, 0xbfb8aa3b, v5
	v_exp_f32_e32 v4, v4
	v_exp_f32_e32 v5, v5
	s_nop 0
	v_pk_add_f32 v[4:5], v[4:5], 1.0 op_sel_hi:[1,0]
	s_nop 0
	v_div_scale_f32 v6, s[20:21], v5, v5, v15
	v_rcp_f32_e32 v7, v6
	s_nop 0
	v_fma_f32 v11, -v6, v7, 1.0
	v_fmac_f32_e32 v7, v11, v7
	v_div_scale_f32 v11, vcc, v15, v5, v15
	v_mul_f32_e32 v12, v11, v7
	v_fma_f32 v13, -v6, v12, v11
	v_fmac_f32_e32 v12, v13, v7
	v_fma_f32 v6, -v6, v12, v11
	v_div_fmas_f32 v6, v6, v7, v12
	v_div_fixup_f32 v5, v6, v5, v15
	v_div_scale_f32 v6, s[20:21], v4, v4, v14
	v_rcp_f32_e32 v7, v6
	s_nop 0
	v_fma_f32 v11, -v6, v7, 1.0
	v_fmac_f32_e32 v7, v11, v7
	v_div_scale_f32 v11, vcc, v14, v4, v14
	v_mul_f32_e32 v12, v11, v7
	v_fma_f32 v13, -v6, v12, v11
	v_fmac_f32_e32 v12, v13, v7
	v_fma_f32 v6, -v6, v12, v11
	v_div_fmas_f32 v6, v6, v7, v12
	v_div_fixup_f32 v4, v6, v4, v14
	v_pk_add_f32 v[68:69], v[68:69], v[4:5]
	ds_read_b128 v[4:7], v10 offset:59152
	s_waitcnt lgkmcnt(0)
	v_div_scale_f32 v10, s[20:21], v1, v1, v5
	v_rcp_f32_e32 v11, v10
	s_nop 0
	v_fma_f32 v12, -v10, v11, 1.0
	v_fmac_f32_e32 v11, v12, v11
	v_div_scale_f32 v12, vcc, v5, v1, v5
	v_mul_f32_e32 v13, v12, v11
	v_fma_f32 v14, -v10, v13, v12
	v_fmac_f32_e32 v13, v14, v11
	v_fma_f32 v10, -v10, v13, v12
	v_div_fmas_f32 v10, v10, v11, v13
	v_div_fixup_f32 v1, v10, v1, v5
	v_div_scale_f32 v5, s[20:21], v0, v0, v4
	v_rcp_f32_e32 v10, v5
	s_nop 0
	v_fma_f32 v11, -v5, v10, 1.0
	v_fmac_f32_e32 v10, v11, v10
	v_div_scale_f32 v11, vcc, v4, v0, v4
	v_mul_f32_e32 v12, v11, v10
	v_fma_f32 v13, -v5, v12, v11
	v_fmac_f32_e32 v12, v13, v10
	v_fma_f32 v5, -v5, v12, v11
	v_div_fmas_f32 v5, v5, v10, v12
	v_div_fixup_f32 v0, v5, v0, v4
	v_pk_add_f32 v[66:67], v[66:67], v[0:1]
	v_add_f32_e32 v0, v2, v9
	v_add_f32_e32 v1, v3, v8
	v_mul_f32_e32 v0, 0xbfb8aa3b, v0
	v_mul_f32_e32 v1, 0xbfb8aa3b, v1
	v_exp_f32_e32 v0, v0
	v_exp_f32_e32 v1, v1
	s_nop 0
	v_pk_add_f32 v[0:1], v[0:1], 1.0 op_sel_hi:[1,0]
	s_nop 0
	v_div_scale_f32 v2, s[20:21], v1, v1, v7
	v_rcp_f32_e32 v3, v2
	s_nop 0
	v_fma_f32 v4, -v2, v3, 1.0
	v_fmac_f32_e32 v3, v4, v3
	v_div_scale_f32 v4, vcc, v7, v1, v7
	v_mul_f32_e32 v5, v4, v3
	v_fma_f32 v8, -v2, v5, v4
	v_fmac_f32_e32 v5, v8, v3
	v_fma_f32 v2, -v2, v5, v4
	v_div_fmas_f32 v2, v2, v3, v5
	v_div_fixup_f32 v1, v2, v1, v7
	v_div_scale_f32 v2, s[20:21], v0, v0, v6
	v_rcp_f32_e32 v3, v2
	s_nop 0
	v_fma_f32 v4, -v2, v3, 1.0
	v_fmac_f32_e32 v3, v4, v3
	v_div_scale_f32 v4, vcc, v6, v0, v6
	v_mul_f32_e32 v5, v4, v3
	v_fma_f32 v7, -v2, v5, v4
	v_fmac_f32_e32 v5, v7, v3
	v_fma_f32 v2, -v2, v5, v4
	v_div_fmas_f32 v2, v2, v3, v5
	v_div_fixup_f32 v0, v2, v0, v6
	v_pk_add_f32 v[64:65], v[64:65], v[0:1]
	s_cbranch_scc0 .LBB0_137
	s_lshl_b64 s[4:5], s[4:5], 18
	v_readlane_b32 s6, v252, 21
	v_readlane_b32 s7, v252, 22
	s_add_u32 s4, s6, s4
	v_mov_b32_e32 v0, v211
	s_addc_u32 s5, s7, s5
	s_lshl_b32 s6, s14, 1
	s_add_u32 s4, s4, s6
	v_ashrrev_i32_e32 v4, 4, v0
	v_lshlrev_b32_e32 v0, 4, v0
	s_addc_u32 s5, s5, 0
	v_and_b32_e32 v208, 0xf0, v0
	v_ashrrev_i32_e32 v5, 31, v4
	v_lshl_add_u64 v[6:7], s[4:5], 0, v[208:209]
	v_lshlrev_b64 v[4:5], 11, v[4:5]
	v_lshl_add_u64 v[4:5], v[6:7], 0, v[4:5]
	s_mov_b32 s4, 0x8000
	v_cvt_pk_bf16_f32 v0, v126, v127
	v_cvt_pk_bf16_f32 v1, v124, v125
	v_cvt_pk_bf16_f32 v2, v120, v121
	v_cvt_pk_bf16_f32 v3, v104, v105
	v_add_co_u32_e32 v6, vcc, s4, v4
	global_store_dwordx4 v[4:5], v[0:3], off
	s_nop 0
	v_addc_co_u32_e32 v7, vcc, 0, v5, vcc
	v_cvt_pk_bf16_f32 v0, v122, v123
	v_cvt_pk_bf16_f32 v1, v118, v119
	v_cvt_pk_bf16_f32 v2, v114, v115
	v_cvt_pk_bf16_f32 v3, v110, v111
	s_mov_b32 s4, 0x10000
	global_store_dwordx4 v[6:7], v[0:3], off
	v_add_co_u32_e32 v6, vcc, s4, v4
	s_nop 0
	v_cvt_pk_bf16_f32 v0, v116, v117
	v_cvt_pk_bf16_f32 v1, v112, v113
	v_cvt_pk_bf16_f32 v2, v106, v107
	v_cvt_pk_bf16_f32 v3, v100, v101
	v_addc_co_u32_e32 v7, vcc, 0, v5, vcc
	s_mov_b32 s2, 0x18000
	global_store_dwordx4 v[6:7], v[0:3], off
	v_add_co_u32_e32 v6, vcc, s2, v4
	s_nop 0
	v_cvt_pk_bf16_f32 v0, v108, v109
	v_cvt_pk_bf16_f32 v1, v102, v103
	v_cvt_pk_bf16_f32 v2, v96, v97
	v_cvt_pk_bf16_f32 v3, v92, v93
	v_addc_co_u32_e32 v7, vcc, 0, v5, vcc
	s_mov_b32 s4, 0x20000
	global_store_dwordx4 v[6:7], v[0:3], off
	v_add_co_u32_e32 v6, vcc, s4, v4
	s_nop 0
	v_cvt_pk_bf16_f32 v0, v98, v99
	v_cvt_pk_bf16_f32 v1, v94, v95
	v_cvt_pk_bf16_f32 v2, v88, v89
	v_cvt_pk_bf16_f32 v3, v84, v85
	v_addc_co_u32_e32 v7, vcc, 0, v5, vcc
	s_mov_b32 s4, 0x28000
	global_store_dwordx4 v[6:7], v[0:3], off
	v_add_co_u32_e32 v6, vcc, s4, v4
	s_nop 0
	v_cvt_pk_bf16_f32 v0, v90, v91
	v_cvt_pk_bf16_f32 v1, v86, v87
	v_cvt_pk_bf16_f32 v2, v82, v83
	v_cvt_pk_bf16_f32 v3, v78, v79
	v_addc_co_u32_e32 v7, vcc, 0, v5, vcc
	s_mov_b32 s4, 0x30000
	global_store_dwordx4 v[6:7], v[0:3], off
	v_add_co_u32_e32 v6, vcc, s4, v4
	s_nop 0
	v_cvt_pk_bf16_f32 v0, v80, v81
	v_addc_co_u32_e32 v7, vcc, 0, v5, vcc
	v_cvt_pk_bf16_f32 v1, v76, v77
	v_cvt_pk_bf16_f32 v2, v74, v75
	v_cvt_pk_bf16_f32 v3, v70, v71
	v_add_co_u32_e32 v4, vcc, 0x38000, v4
	global_store_dwordx4 v[6:7], v[0:3], off
	s_nop 0
	v_addc_co_u32_e32 v5, vcc, 0, v5, vcc
	v_cvt_pk_bf16_f32 v0, v72, v73
	v_cvt_pk_bf16_f32 v1, v68, v69
	v_cvt_pk_bf16_f32 v2, v66, v67
	v_cvt_pk_bf16_f32 v3, v64, v65
	global_store_dwordx4 v[4:5], v[0:3], off
	s_barrier
	s_and_saveexec_b64 s[4:5], s[36:37]
	s_cbranch_execz .LBB0_131
	v_readlane_b32 s6, v253, 62
	s_nop 1
	v_mov_b32_e32 v0, s6
	ds_write_b32 v0, v144
	s_branch .LBB0_131
